# attention inner loop hand-rewritten: LDS-DMA 4-stage ring, prefetched LDS frags, even VALU/MFMA interleave; same math order
# speedup vs baseline: 1.0330x; 1.0330x over previous
; #define LAS __attribute__((address_space(3)))
; DEV void attn_unit(int b, int h, int qb, const bf16_t* Q, const bf16_t* K, const bf16_t* V, bf16_t* O, LAS unsigned char* sh, const int tid, const float* qgain) {
;     const int lane = tid & 63, r32 = lane & 31, hi = lane >> 5; const int wid = __builtin_amdgcn_readfirstlane(tid >> 6);
;     const long qrow0 = (long)b * SEQ + qb * 256 + wid * 32;
;     const bf16_t* Qw = Q + qrow0 * 1536 + h * 96;
;     const unsigned lds0 = (unsigned)(uintptr_t)sh;
;     LAS float* wsf = (LAS float*)(sh + OFF_WS) + wid * 64;
;     bf16x8 qr[6];
; #pragma unroll
;     for (int d0 = 0; d0 < 6; ++d0) qr[d0] = *(const bf16x8*)(Qw + (long)r32 * 1536 + d0 * 16 + hi * 8);
;     {
;         float qv[6][8]; float ss = 0.f;
; #pragma unroll
;         for (int d0 = 0; d0 < 6; ++d0) { const u32x4 raw = __builtin_bit_cast(u32x4, qr[d0]);
;             qv[d0][0] = __uint_as_float(raw.x << 16); qv[d0][1] = __uint_as_float(raw.x & 0xffff0000u); qv[d0][2] = __uint_as_float(raw.y << 16); qv[d0][3] = __uint_as_float(raw.y & 0xffff0000u);
;             qv[d0][4] = __uint_as_float(raw.z << 16); qv[d0][5] = __uint_as_float(raw.z & 0xffff0000u); qv[d0][6] = __uint_as_float(raw.w << 16); qv[d0][7] = __uint_as_float(raw.w & 0xffff0000u);
; #pragma unroll
;             for (int e = 0; e < 8; ++e) ss += qv[d0][e] * qv[d0][e]; }
;         ss += __shfl_xor(ss, 32);
;         const float rstd = 1.0f / sqrtf(ss * (1.f / 96.f) + EPS);
; template <int LO, int HI>
; DEV void run_phases(LAS unsigned char* lds, const int ph_lo, const int ph_hi, const int G, const int wave0, unsigned& nbar) {
;     ...
;                 int un = vcu * per + k;
;                 if (G == 256) {
;                     const int xcd = vcu >> 5, loc = vcu & 31; un = ((xcd * 16 + 2 * k + (loc >> 4)) << 4) | (loc & 15); }
;                 if (un >= 2048) break;
;                 const int bh = un >> 4, qb = un & 15;
.LBB0_2104:
	s_lshl_b32 s4, s31, 5
	s_add_i32 s7, s30, s4
	v_readlane_b32 s4, v248, 2
	s_add_i32 s6, s31, s1
	v_readlane_b32 s5, v248, 3
	s_and_b64 s[4:5], s[4:5], exec
	s_cselect_b32 s18, s7, s6
	s_cmpk_gt_i32 s18, 0x7ff
	s_mov_b64 s[4:5], -1
	s_cbranch_scc1 .LBB0_2103
	s_ashr_i32 s4, s18, 8
	v_readfirstlane_b32 s19, v135
	s_ashr_i32 s5, s4, 31
	s_ashr_i32 s21, s19, 6
	s_lshl_b64 s[8:9], s[4:5], 12
	s_lshl_b32 s4, s18, 8
	v_readlane_b32 s6, v251, 31
	s_and_b32 s15, s4, 0xf00
	s_lshl_b32 s14, s21, 5
	s_bfe_u32 s20, s18, 0x40004
	v_readlane_b32 s7, v251, 32
	s_or_b32 s4, s8, s15
	s_ashr_i32 s5, s14, 31
	s_load_dwordx2 s[12:13], s[6:7], 0xf0
	s_add_u32 s6, s4, s14
	s_addc_u32 s7, s9, s5
	s_mul_i32 s4, s7, 0xc00
	s_mul_hi_u32 s5, s6, 0xc00
	s_add_i32 s5, s5, s4
	s_mul_i32 s4, s6, 0xc00
	v_readlane_b32 s10, v251, 54
	v_readlane_b32 s11, v251, 55
	s_add_u32 s4, s10, s4
	s_mul_i32 s10, s20, 0x60
	s_addc_u32 s5, s11, s5
	s_lshl_b32 s10, s10, 1
	s_add_u32 s4, s4, s10
	s_addc_u32 s5, s5, 0
	v_mov_b32_e32 v141, v97
	v_lshl_add_u64 v[0:1], s[4:5], 0, v[140:141]
	v_lshlrev_b32_e32 v96, 1, v134
	v_lshl_add_u64 v[16:17], v[0:1], 0, v[96:97]
	global_load_dwordx4 v[0:3], v[16:17], off
	global_load_dwordx4 v[4:7], v[16:17], off offset:32
	global_load_dwordx4 v[8:11], v[16:17], off offset:64
	global_load_dwordx4 v[12:15], v[16:17], off offset:96
	global_load_dwordx4 v[50:53], v[16:17], off offset:128
	global_load_dwordx4 v[54:57], v[16:17], off offset:160
	v_xor_b32_e32 v40, 32, v183
	s_mov_b32 s11, s88
	s_waitcnt vmcnt(5)
	v_and_b32_e32 v17, 0xffff0000, v0
	v_lshlrev_b32_e32 v16, 16, v0
	v_mul_f32_e32 v18, v17, v17
	v_lshlrev_b32_e32 v19, 16, v1
	v_fmac_f32_e32 v18, v16, v16
	v_and_b32_e32 v21, 0xffff0000, v1
	v_fmac_f32_e32 v18, v19, v19
	v_lshlrev_b32_e32 v20, 16, v2
	v_fmac_f32_e32 v18, v21, v21
	v_and_b32_e32 v22, 0xffff0000, v2
	v_fmac_f32_e32 v18, v20, v20
	v_lshlrev_b32_e32 v23, 16, v3
	v_fmac_f32_e32 v18, v22, v22
	v_and_b32_e32 v26, 0xffff0000, v3
	v_fmac_f32_e32 v18, v23, v23
	v_fmac_f32_e32 v18, v26, v26
	s_waitcnt vmcnt(4)
	v_lshlrev_b32_e32 v24, 16, v4
	v_and_b32_e32 v25, 0xffff0000, v4
	v_fmac_f32_e32 v18, v24, v24
	v_lshlrev_b32_e32 v27, 16, v5
	v_fmac_f32_e32 v18, v25, v25
	v_and_b32_e32 v29, 0xffff0000, v5
	v_fmac_f32_e32 v18, v27, v27
	v_lshlrev_b32_e32 v28, 16, v6
	v_fmac_f32_e32 v18, v29, v29
	v_and_b32_e32 v30, 0xffff0000, v6
	v_fmac_f32_e32 v18, v28, v28
	v_lshlrev_b32_e32 v31, 16, v7
	v_fmac_f32_e32 v18, v30, v30
	v_and_b32_e32 v34, 0xffff0000, v7
	v_fmac_f32_e32 v18, v31, v31
	v_fmac_f32_e32 v18, v34, v34
	s_waitcnt vmcnt(3)
	v_lshlrev_b32_e32 v32, 16, v8
	v_and_b32_e32 v33, 0xffff0000, v8
	v_fmac_f32_e32 v18, v32, v32
	v_lshlrev_b32_e32 v35, 16, v9
	v_fmac_f32_e32 v18, v33, v33
	v_and_b32_e32 v37, 0xffff0000, v9
	v_fmac_f32_e32 v18, v35, v35
	v_lshlrev_b32_e32 v36, 16, v10
	v_fmac_f32_e32 v18, v37, v37
	v_and_b32_e32 v38, 0xffff0000, v10
	v_fmac_f32_e32 v18, v36, v36
	v_lshlrev_b32_e32 v39, 16, v11
	v_fmac_f32_e32 v18, v38, v38
	v_and_b32_e32 v49, 0xffff0000, v11
	v_fmac_f32_e32 v18, v39, v39
	v_fmac_f32_e32 v18, v49, v49
	s_waitcnt vmcnt(2)
	v_lshlrev_b32_e32 v47, 16, v12
	v_and_b32_e32 v45, 0xffff0000, v12
	v_fmac_f32_e32 v18, v47, v47
	v_lshlrev_b32_e32 v43, 16, v13
	v_fmac_f32_e32 v18, v45, v45
	v_and_b32_e32 v41, 0xffff0000, v13
	v_fmac_f32_e32 v18, v43, v43
	v_lshlrev_b32_e32 v48, 16, v14
	v_fmac_f32_e32 v18, v41, v41
	v_and_b32_e32 v46, 0xffff0000, v14
	v_fmac_f32_e32 v18, v48, v48
	v_lshlrev_b32_e32 v44, 16, v15
	v_fmac_f32_e32 v18, v46, v46
	v_and_b32_e32 v42, 0xffff0000, v15
	v_fmac_f32_e32 v18, v44, v44
	v_fmac_f32_e32 v18, v42, v42
	s_waitcnt vmcnt(1)
	v_lshlrev_b32_e32 v6, 16, v50
	v_and_b32_e32 v4, 0xffff0000, v50
	v_fmac_f32_e32 v18, v6, v6
	v_lshlrev_b32_e32 v2, 16, v51
	v_fmac_f32_e32 v18, v4, v4
	v_and_b32_e32 v0, 0xffff0000, v51
	v_fmac_f32_e32 v18, v2, v2
	v_lshlrev_b32_e32 v7, 16, v52
	v_fmac_f32_e32 v18, v0, v0
	v_and_b32_e32 v5, 0xffff0000, v52
	v_fmac_f32_e32 v18, v7, v7
	v_lshlrev_b32_e32 v3, 16, v53
	v_fmac_f32_e32 v18, v5, v5
	v_and_b32_e32 v1, 0xffff0000, v53
	v_fmac_f32_e32 v18, v3, v3
	v_fmac_f32_e32 v18, v1, v1
	s_waitcnt vmcnt(0)
	v_lshlrev_b32_e32 v14, 16, v54
	v_and_b32_e32 v12, 0xffff0000, v54
	v_fmac_f32_e32 v18, v14, v14
	v_lshlrev_b32_e32 v11, 16, v55
	v_fmac_f32_e32 v18, v12, v12
	v_and_b32_e32 v10, 0xffff0000, v55
	v_fmac_f32_e32 v18, v11, v11
	v_lshlrev_b32_e32 v15, 16, v56
	v_fmac_f32_e32 v18, v10, v10
	v_and_b32_e32 v13, 0xffff0000, v56
	v_fmac_f32_e32 v18, v15, v15
	v_and_b32_e32 v8, 0xffff0000, v57
	v_lshlrev_b32_e32 v9, 16, v57
	v_fmac_f32_e32 v18, v13, v13
	v_pk_mul_f32 v[50:51], v[8:9], v[8:9]
	s_nop 0
	v_add_f32_e32 v18, v51, v18
	v_add_f32_e32 v18, v50, v18
	v_and_b32_e32 v50, 64, v183
	v_add_u32_e32 v50, 64, v50
	v_cmp_lt_i32_e32 vcc, v40, v50
	s_nop 1
	v_cndmask_b32_e32 v40, v183, v40, vcc
	v_lshlrev_b32_e32 v141, 2, v40
	ds_bpermute_b32 v40, v141, v18
	s_waitcnt lgkmcnt(0)
	v_add_f32_e32 v18, v18, v40
	v_fmamk_f32 v18, v18, 0x3c2aaaab, v180
	v_cmp_gt_f32_e32 vcc, s78, v18
	v_mul_f32_e32 v40, 0x4f800000, v18
	s_nop 0
	v_cndmask_b32_e32 v18, v18, v40, vcc
	v_sqrt_f32_e32 v40, v18
	s_nop 0
	v_add_u32_e32 v50, -1, v40
	v_fma_f32 v51, -v50, v40, v18
	v_cmp_ge_f32_e64 s[4:5], 0, v51
	v_add_u32_e32 v51, 1, v40
	s_nop 0
	v_cndmask_b32_e64 v50, v40, v50, s[4:5]
	v_fma_f32 v40, -v51, v40, v18
	v_cmp_lt_f32_e64 s[4:5], 0, v40
	s_nop 1
	v_cndmask_b32_e64 v40, v50, v51, s[4:5]
	v_mul_f32_e32 v50, 0x37800000, v40
	v_cndmask_b32_e32 v40, v40, v50, vcc
	v_cmp_class_f32_e32 vcc, v18, v181
	s_nop 1
	v_cndmask_b32_e32 v18, v40, v18, vcc
	v_div_scale_f32 v40, s[4:5], v18, v18, 1.0
	v_rcp_f32_e32 v50, v40
	s_add_i32 s4, s14, s15
	s_ashr_i32 s4, s4, 6
	s_cmp_lt_i32 s21, 4
	v_fma_f32 v51, -v40, v50, 1.0
	v_fmac_f32_e32 v50, v51, v50
	v_div_scale_f32 v51, vcc, 1.0, v18, 1.0
	v_mul_f32_e32 v52, v51, v50
	v_fma_f32 v53, -v40, v52, v51
	v_fmac_f32_e32 v52, v53, v50
	v_fma_f32 v40, -v40, v52, v51
	v_div_fmas_f32 v40, v40, v50, v52
	v_lshlrev_b32_e32 v50, 2, v134
	global_load_dwordx4 v[52:55], v50, s[12:13] offset:16
	global_load_dwordx4 v[56:59], v50, s[12:13]
	v_div_fixup_f32 v40, v40, v18, 1.0
	s_cselect_b64 s[16:17], -1, 0
	s_waitcnt vmcnt(0)
; DEV void attn_unit(int b, int h, int qb, const bf16_t* Q, const bf16_t* K, const bf16_t* V, bf16_t* O, LAS unsigned char* sh, const int tid, const float* qgain) {
;     ...
; #pragma unroll
;         for (int d0 = 0; d0 < 6; ++d0) { const f32x4 g0 = *(const f32x4*)(qgain + d0 * 16 + hi * 8), g1 = *(const f32x4*)(qgain + d0 * 16 + hi * 8 + 4);
; #pragma unroll
;             for (int e = 0; e < 4; ++e) { qv[d0][e] *= rstd * g0[e]; qv[d0][4 + e] *= rstd * g1[e]; } }
;         const int tq = qb * 256 + wid * 32 + r32; const float pr = (float)(tq >> 6), pc = (float)(tq & 63);
; #pragma unroll
;         for (int e = 0; e < 8; ++e) { const float invf = exp2f(-(float)e * (13.287712379549449f / 8.f));
;             const float rr_ = pr * invf * 0.15915494309189535f, rc_ = pc * invf * 0.15915494309189535f;
;             const float sr = __builtin_amdgcn_sinf(rr_), cr = __builtin_amdgcn_cosf(rr_), sc_ = __builtin_amdgcn_sinf(rc_), cc = __builtin_amdgcn_cosf(rc_);
;             const float o4 = qv[4][e], o5 = qv[5][e], p4 = __shfl_xor(o4, 32), p5 = __shfl_xor(o5, 32);
;             qv[4][e] = hi ? (p4 * sr + o4 * cr) : (o4 * cr - p4 * sr);
;             qv[5][e] = hi ? (p5 * sc_ + o5 * cc) : (o5 * cc - p5 * sc_); }
	v_mul_f32_e32 v18, v56, v40
	v_mul_f32_e32 v18, v18, v16
	v_mul_f32_e32 v16, v52, v40
	v_mul_f32_e32 v16, v16, v20
	v_mul_f32_e32 v20, v57, v40
	v_mul_f32_e32 v20, v20, v17
	v_mul_f32_e32 v17, v53, v40
	v_mul_f32_e32 v17, v17, v22
	v_mul_f32_e32 v22, v58, v40
	v_mul_f32_e32 v22, v22, v19
	v_mul_f32_e32 v19, v54, v40
	v_mul_f32_e32 v19, v19, v23
	v_mul_f32_e32 v23, v59, v40
	v_mul_f32_e32 v23, v23, v21
	v_mul_f32_e32 v21, v55, v40
	global_load_dwordx4 v[52:55], v50, s[12:13] offset:80
	global_load_dwordx4 v[56:59], v50, s[12:13] offset:64
	v_mul_f32_e32 v21, v21, v26
	s_waitcnt vmcnt(0)
	v_mul_f32_e32 v26, v56, v40
	v_mul_f32_e32 v26, v26, v24
	v_mul_f32_e32 v24, v52, v40
	v_mul_f32_e32 v24, v24, v28
	v_mul_f32_e32 v28, v57, v40
	v_mul_f32_e32 v28, v28, v25
	v_mul_f32_e32 v25, v53, v40
	v_mul_f32_e32 v25, v25, v30
	v_mul_f32_e32 v30, v58, v40
	v_mul_f32_e32 v30, v30, v27
	v_mul_f32_e32 v27, v54, v40
	v_mul_f32_e32 v27, v27, v31
	v_mul_f32_e32 v31, v59, v40
	v_mul_f32_e32 v31, v31, v29
	v_mul_f32_e32 v29, v55, v40
	global_load_dwordx4 v[52:55], v50, s[12:13] offset:144
	global_load_dwordx4 v[56:59], v50, s[12:13] offset:128
	v_mul_f32_e32 v29, v29, v34
	s_waitcnt vmcnt(0)
	v_mul_f32_e32 v34, v56, v40
	v_mul_f32_e32 v34, v34, v32
	v_mul_f32_e32 v32, v52, v40
	v_mul_f32_e32 v32, v32, v36
	v_mul_f32_e32 v36, v57, v40
	v_mul_f32_e32 v36, v36, v33
	v_mul_f32_e32 v33, v53, v40
	v_mul_f32_e32 v33, v33, v38
	v_mul_f32_e32 v38, v58, v40
	v_mul_f32_e32 v38, v38, v35
	v_mul_f32_e32 v35, v54, v40
	v_mul_f32_e32 v35, v35, v39
	v_mul_f32_e32 v39, v59, v40
	v_mul_f32_e32 v39, v39, v37
	v_mul_f32_e32 v37, v55, v40
	global_load_dwordx4 v[52:55], v50, s[12:13] offset:208
	global_load_dwordx4 v[56:59], v50, s[12:13] offset:192
	v_mul_f32_e32 v37, v37, v49
	s_waitcnt vmcnt(0)
	v_mul_f32_e32 v49, v56, v40
	v_mul_f32_e32 v49, v49, v47
	v_mul_f32_e32 v47, v52, v40
	v_mul_f32_e32 v47, v47, v48
	v_mul_f32_e32 v48, v57, v40
	v_mul_f32_e32 v48, v48, v45
	v_mul_f32_e32 v45, v53, v40
	v_mul_f32_e32 v45, v45, v46
	v_mul_f32_e32 v46, v58, v40
	v_mul_f32_e32 v46, v46, v43
	v_mul_f32_e32 v43, v54, v40
	v_mul_f32_e32 v43, v43, v44
	v_mul_f32_e32 v44, v59, v40
	global_load_dwordx4 v[58:61], v50, s[12:13] offset:272
	global_load_dwordx4 v[62:65], v50, s[12:13] offset:256
	v_mul_f32_e32 v44, v44, v41
	v_mul_f32_e32 v41, v55, v40
	v_mul_f32_e32 v41, v41, v42
	s_waitcnt vmcnt(0)
	v_mul_f32_e32 v42, v62, v40
	v_mul_f32_e32 v57, v42, v6
	v_mul_f32_e32 v6, v58, v40
	v_mul_f32_e32 v53, v6, v7
	v_mul_f32_e32 v6, v63, v40
	v_mul_f32_e32 v56, v6, v4
	v_mul_f32_e32 v4, v59, v40
	v_mul_f32_e32 v52, v4, v5
	v_mul_f32_e32 v4, v64, v40
	v_mul_f32_e32 v55, v4, v2
	v_mul_f32_e32 v2, v60, v40
	v_mul_f32_e32 v51, v2, v3
	v_mul_f32_e32 v2, v65, v40
	v_mul_f32_e32 v54, v2, v0
	v_mul_f32_e32 v0, v61, v40
	v_mul_f32_e32 v42, v0, v1
	global_load_dwordx4 v[0:3], v50, s[12:13] offset:336
	global_load_dwordx4 v[4:7], v50, s[12:13] offset:320
	s_waitcnt vmcnt(1)
	v_mul_f32_e32 v3, v3, v40
	v_mul_f32_e32 v3, v3, v8
	v_cvt_f32_i32_e32 v8, s4
	s_waitcnt vmcnt(0)
	v_mul_f32_e32 v4, v4, v40
	v_mul_f32_e32 v2, v2, v40
	v_mul_f32_e32 v7, v7, v40
	v_mul_f32_e32 v4, v4, v14
	v_mul_f32_e32 v5, v5, v40
	v_mul_f32_e32 v2, v2, v9
	v_mul_f32_e32 v7, v7, v10
	v_and_or_b32 v9, s14, 32, v132
	v_mul_f32_e32 v10, 0.15915494, v8
	ds_bpermute_b32 v14, v141, v57
	v_mul_f32_e32 v0, v0, v40
	v_mul_f32_e32 v5, v5, v12
	v_mul_f32_e32 v6, v6, v40
	v_cvt_f32_ubyte0_e32 v9, v9
	v_sin_f32_e32 v12, v10
	v_mul_f32_e32 v0, v0, v15
	v_mul_f32_e32 v1, v1, v40
	v_mul_f32_e32 v6, v6, v11
	v_mul_f32_e32 v11, 0.15915494, v9
	ds_bpermute_b32 v15, v141, v4
	v_mul_f32_e32 v1, v1, v13
	v_cos_f32_e32 v10, v10
	v_sin_f32_e32 v13, v11
	v_cos_f32_e32 v11, v11
	s_waitcnt lgkmcnt(1)
	v_mul_f32_e32 v12, v12, v14
	v_cndmask_b32_e64 v12, v12, -v12, s[2:3]
	v_fmac_f32_e32 v12, v10, v57
	s_waitcnt lgkmcnt(0)
	v_mul_f32_e32 v10, v13, v15
	v_cndmask_b32_e64 v10, v10, -v10, s[2:3]
	v_fmac_f32_e32 v10, v11, v4
	v_mul_f32_e32 v4, 0x3ea1e89b, v8
	v_mul_f32_e32 v4, 0.15915494, v4
	ds_bpermute_b32 v15, v141, v56
	v_mul_f32_e32 v11, 0x3ea1e89b, v9
	v_sin_f32_e32 v13, v4
	v_mul_f32_e32 v11, 0.15915494, v11
	ds_bpermute_b32 v40, v141, v5
	v_cos_f32_e32 v4, v4
	v_sin_f32_e32 v14, v11
	v_cos_f32_e32 v11, v11
	s_waitcnt lgkmcnt(1)
	v_mul_f32_e32 v13, v13, v15
	v_cndmask_b32_e64 v13, v13, -v13, s[2:3]
	v_fmac_f32_e32 v13, v4, v56
	s_waitcnt lgkmcnt(0)
	v_mul_f32_e32 v4, v14, v40
	v_cndmask_b32_e64 v4, v4, -v4, s[2:3]
	v_fmac_f32_e32 v4, v11, v5
	v_mul_f32_e32 v5, 0x3dcccccd, v8
	v_mul_f32_e32 v5, 0.15915494, v5
	ds_bpermute_b32 v40, v141, v55
	v_mul_f32_e32 v11, 0x3dcccccd, v9
	v_sin_f32_e32 v14, v5
	v_mul_f32_e32 v11, 0.15915494, v11
	ds_bpermute_b32 v50, v141, v6
	v_cos_f32_e32 v5, v5
	v_sin_f32_e32 v15, v11
	v_cos_f32_e32 v11, v11
	s_waitcnt lgkmcnt(1)
	v_mul_f32_e32 v14, v14, v40
	v_cndmask_b32_e64 v14, v14, -v14, s[2:3]
	v_fmac_f32_e32 v14, v5, v55
	s_waitcnt lgkmcnt(0)
	v_mul_f32_e32 v5, v15, v50
	v_cndmask_b32_e64 v5, v5, -v5, s[2:3]
	v_fmac_f32_e32 v5, v11, v6
	v_mul_f32_e32 v6, 0x3d0186e3, v8
	v_mul_f32_e32 v6, 0.15915494, v6
	ds_bpermute_b32 v50, v141, v54
	v_mul_f32_e32 v11, 0x3d0186e3, v9
	v_sin_f32_e32 v15, v6
	v_mul_f32_e32 v11, 0.15915494, v11
	ds_bpermute_b32 v55, v141, v7
	v_cos_f32_e32 v6, v6
	v_sin_f32_e32 v40, v11
	v_cos_f32_e32 v11, v11
	s_waitcnt lgkmcnt(1)
	v_mul_f32_e32 v15, v15, v50
	v_cndmask_b32_e64 v15, v15, -v15, s[2:3]
	v_fmac_f32_e32 v15, v6, v54
	s_waitcnt lgkmcnt(0)
; DEV unsigned cvt_pk_bf16(float lo, float hi) { unsigned r; asm volatile("v_cvt_pk_bf16_f32 %0, %1, %2" : "=v"(r) : "v"(lo), "v"(hi)); return r; }
; DEV void attn_unit(int b, int h, int qb, const bf16_t* Q, const bf16_t* K, const bf16_t* V, bf16_t* O, LAS unsigned char* sh, const int tid, const float* qgain) {
;     ...
;             const float o4 = qv[4][e], o5 = qv[5][e], p4 = __shfl_xor(o4, 32), p5 = __shfl_xor(o5, 32);
;             qv[4][e] = hi ? (p4 * sr + o4 * cr) : (o4 * cr - p4 * sr);
;             qv[5][e] = hi ? (p5 * sc_ + o5 * cc) : (o5 * cc - p5 * sc_); }
; #pragma unroll
;         for (int d0 = 0; d0 < 6; ++d0) { u32x4 w; w.x = cvt_pk_bf16(qv[d0][0] * QSCALE, qv[d0][1] * QSCALE); w.y = cvt_pk_bf16(qv[d0][2] * QSCALE, qv[d0][3] * QSCALE);
;             w.z = cvt_pk_bf16(qv[d0][4] * QSCALE, qv[d0][5] * QSCALE); w.w = cvt_pk_bf16(qv[d0][6] * QSCALE, qv[d0][7] * QSCALE); qr[d0] = __builtin_bit_cast(bf16x8, w); }
;     ...
;     const bool k2 = wid < 4;
;     ...
;     float mrun = 0.f, lsum = 0.f; f32x16 o[2]; o[0] = f32x16{}; o[1] = f32x16{}; const f32x16 zero16 = f32x16{};
	v_mul_f32_e32 v6, v40, v55
	v_cndmask_b32_e64 v6, v6, -v6, s[2:3]
	v_fmac_f32_e32 v6, v11, v7
	v_mul_f32_e32 v7, 0x3c23d70b, v8
	v_mul_f32_e32 v7, 0.15915494, v7
	ds_bpermute_b32 v54, v141, v53
	v_mul_f32_e32 v11, 0x3c23d70b, v9
	v_sin_f32_e32 v40, v7
	v_mul_f32_e32 v11, 0.15915494, v11
	ds_bpermute_b32 v55, v141, v0
	v_cos_f32_e32 v7, v7
	v_sin_f32_e32 v50, v11
	v_cos_f32_e32 v11, v11
	s_waitcnt lgkmcnt(1)
	v_mul_f32_e32 v40, v40, v54
	v_cndmask_b32_e64 v40, v40, -v40, s[2:3]
	v_fmac_f32_e32 v40, v7, v53
	s_waitcnt lgkmcnt(0)
	v_mul_f32_e32 v7, v50, v55
	v_cndmask_b32_e64 v7, v7, -v7, s[2:3]
	v_fmac_f32_e32 v7, v11, v0
	v_mul_f32_e32 v0, 0x3b4f3e39, v8
	v_mul_f32_e32 v0, 0.15915494, v0
	ds_bpermute_b32 v54, v141, v52
	v_mul_f32_e32 v11, 0x3b4f3e39, v9
	v_sin_f32_e32 v50, v0
	v_mul_f32_e32 v11, 0.15915494, v11
	ds_bpermute_b32 v55, v141, v1
	v_cos_f32_e32 v0, v0
	v_sin_f32_e32 v53, v11
	v_cos_f32_e32 v11, v11
	s_waitcnt lgkmcnt(1)
	v_mul_f32_e32 v50, v50, v54
	v_cndmask_b32_e64 v50, v50, -v50, s[2:3]
	v_fmac_f32_e32 v50, v0, v52
	s_waitcnt lgkmcnt(0)
	v_mul_f32_e32 v0, v53, v55
	v_cndmask_b32_e64 v0, v0, -v0, s[2:3]
	v_fmac_f32_e32 v0, v11, v1
	v_mul_f32_e32 v1, 0x3a831270, v8
	v_mul_f32_e32 v1, 0.15915494, v1
	ds_bpermute_b32 v54, v141, v51
	v_mul_f32_e32 v11, 0x3a831270, v9
	v_sin_f32_e32 v52, v1
	v_mul_f32_e32 v11, 0.15915494, v11
	ds_bpermute_b32 v55, v141, v2
	v_cos_f32_e32 v1, v1
	v_sin_f32_e32 v53, v11
	v_cos_f32_e32 v11, v11
	s_waitcnt lgkmcnt(1)
	v_mul_f32_e32 v52, v52, v54
	v_cndmask_b32_e64 v52, v52, -v52, s[2:3]
	v_fmac_f32_e32 v52, v1, v51
	s_waitcnt lgkmcnt(0)
	v_mul_f32_e32 v1, v53, v55
	v_cndmask_b32_e64 v1, v1, -v1, s[2:3]
	v_fmac_f32_e32 v1, v11, v2
	v_mul_f32_e32 v2, 0x39a5cb61, v8
	v_mul_f32_e32 v2, 0.15915494, v2
	ds_bpermute_b32 v51, v141, v42
	v_mul_f32_e32 v8, 0x39a5cb61, v9
	v_sin_f32_e32 v9, v2
	v_mul_f32_e32 v8, 0.15915494, v8
	ds_bpermute_b32 v53, v141, v3
	v_cos_f32_e32 v2, v2
	v_sin_f32_e32 v11, v8
	v_cos_f32_e32 v8, v8
	s_waitcnt lgkmcnt(1)
	v_mul_f32_e32 v9, v9, v51
	v_cndmask_b32_e64 v9, v9, -v9, s[2:3]
	v_fmac_f32_e32 v9, v2, v42
	s_waitcnt lgkmcnt(0)
	v_mul_f32_e32 v2, v11, v53
	v_cndmask_b32_e64 v2, v2, -v2, s[2:3]
	v_fmac_f32_e32 v2, v8, v3
	v_mul_f32_e32 v3, 0x3e16c740, v18
	v_mul_f32_e32 v8, 0x3e16c740, v20
	v_cvt_pk_bf16_f32 v110, v3, v8
	v_mul_f32_e32 v3, 0x3e16c740, v22
	v_mul_f32_e32 v8, 0x3e16c740, v23
	v_cvt_pk_bf16_f32 v111, v3, v8
	v_mul_f32_e32 v3, 0x3e16c740, v16
	v_mul_f32_e32 v8, 0x3e16c740, v17
	v_cvt_pk_bf16_f32 v112, v3, v8
	v_mul_f32_e32 v3, 0x3e16c740, v19
	v_mul_f32_e32 v8, 0x3e16c740, v21
	v_cvt_pk_bf16_f32 v113, v3, v8
	v_mul_f32_e32 v3, 0x3e16c740, v26
	v_mul_f32_e32 v8, 0x3e16c740, v28
	v_cvt_pk_bf16_f32 v106, v3, v8
	v_mul_f32_e32 v3, 0x3e16c740, v30
	v_mul_f32_e32 v8, 0x3e16c740, v31
	v_cvt_pk_bf16_f32 v107, v3, v8
	v_mul_f32_e32 v3, 0x3e16c740, v24
	v_mul_f32_e32 v8, 0x3e16c740, v25
	v_cvt_pk_bf16_f32 v108, v3, v8
	v_mul_f32_e32 v3, 0x3e16c740, v27
	v_mul_f32_e32 v8, 0x3e16c740, v29
	v_cvt_pk_bf16_f32 v109, v3, v8
	v_mul_f32_e32 v3, 0x3e16c740, v34
	v_mul_f32_e32 v8, 0x3e16c740, v36
	v_cvt_pk_bf16_f32 v114, v3, v8
	v_mul_f32_e32 v3, 0x3e16c740, v38
	v_mul_f32_e32 v8, 0x3e16c740, v39
	v_cvt_pk_bf16_f32 v115, v3, v8
	v_mul_f32_e32 v3, 0x3e16c740, v32
	v_mul_f32_e32 v8, 0x3e16c740, v33
	v_cvt_pk_bf16_f32 v116, v3, v8
	v_mul_f32_e32 v3, 0x3e16c740, v35
	v_mul_f32_e32 v8, 0x3e16c740, v37
	v_cvt_pk_bf16_f32 v117, v3, v8
	v_mul_f32_e32 v3, 0x3e16c740, v49
	v_mul_f32_e32 v8, 0x3e16c740, v48
	v_cvt_pk_bf16_f32 v118, v3, v8
	v_mul_f32_e32 v3, 0x3e16c740, v46
	v_mul_f32_e32 v8, 0x3e16c740, v44
	v_cvt_pk_bf16_f32 v119, v3, v8
	v_mul_f32_e32 v3, 0x3e16c740, v47
	v_mul_f32_e32 v8, 0x3e16c740, v45
	v_cvt_pk_bf16_f32 v120, v3, v8
	v_mul_f32_e32 v3, 0x3e16c740, v43
	v_mul_f32_e32 v8, 0x3e16c740, v41
	v_cvt_pk_bf16_f32 v121, v3, v8
	v_mul_f32_e32 v3, 0x3e16c740, v12
	v_mul_f32_e32 v8, 0x3e16c740, v13
	v_cvt_pk_bf16_f32 v102, v3, v8
	v_mul_f32_e32 v3, 0x3e16c740, v14
	v_mul_f32_e32 v8, 0x3e16c740, v15
	v_cvt_pk_bf16_f32 v103, v3, v8
	v_mul_f32_e32 v3, 0x3e16c740, v40
	v_mul_f32_e32 v8, 0x3e16c740, v50
	v_cvt_pk_bf16_f32 v104, v3, v8
	v_mul_f32_e32 v3, 0x3e16c740, v52
	v_mul_f32_e32 v8, 0x3e16c740, v9
	v_cvt_pk_bf16_f32 v105, v3, v8
	v_mul_f32_e32 v3, 0x3e16c740, v10
	v_mul_f32_e32 v4, 0x3e16c740, v4
	v_cvt_pk_bf16_f32 v98, v3, v4
	v_mul_f32_e32 v3, 0x3e16c740, v5
	v_mul_f32_e32 v0, 0x3e16c740, v0
	v_readlane_b32 s4, v251, 44
	v_mul_f32_e32 v4, 0x3e16c740, v6
	v_cvt_pk_bf16_f32 v99, v3, v4
	v_mul_f32_e32 v3, 0x3e16c740, v7
	v_cvt_pk_bf16_f32 v100, v3, v0
	v_mul_f32_e32 v0, 0x3e16c740, v1
	v_mul_f32_e32 v1, 0x3e16c740, v2
	v_readlane_b32 s5, v251, 45
	v_cvt_pk_bf16_f32 v101, v0, v1
	s_lshl_b32 s33, s21, 8
	s_lshl_b32 s22, s21, 10
	s_cmp_lt_u32 s21, 4
	s_cselect_b32 s23, 1, 0
	v_lshl_add_u32 v143, v132, 2, s33
	s_lshl_b32 s27, s20, 7
	s_mul_i32 s4, s8, 0xc00
	s_mul_i32 s5, s20, 0xc0
	s_lshl_b32 s25, s21, 4
	s_add_u32 s5, s5, s25
	s_add_u32 s4, s4, s5
	s_lshr_b32 s25, s8, 4
	s_add_u32 s25, s25, 0x8000
	s_mul_i32 s26, s25, 0xc00
	s_add_u32 s26, s26, s5
	v_readlane_b32 s12, v251, 44
	v_readlane_b32 s13, v251, 45
	v_mul_u32_u24_e32 v128, 0xc00, v130
	v_lshlrev_b32_e32 v145, 11, v136
	s_add_u32 s36, s12, s26
	s_addc_u32 s37, s13, 0
	s_add_u32 s12, s12, s4
	s_addc_u32 s13, s13, 0
	s_and_b32 s5, s21, 3
	s_lshl_b32 s5, s5, 4
	s_add_u32 s4, s8, s5
	s_lshl_b32 s4, s4, 11
	s_lshr_b32 s34, s21, 2
	s_lshl_b32 s34, s34, 6
	s_add_u32 s34, s34, s27
	s_add_u32 s4, s4, s34
	s_add_u32 s25, s25, s5
	s_lshl_b32 s25, s25, 11
	s_add_u32 s25, s25, s34
	v_readlane_b32 s14, v251, 35
	v_readlane_b32 s15, v251, 36
	v_add_u32_e32 v129, 0x80, v128
	v_lshl_add_u32 v145, v138, 1, v145
	s_add_u32 s38, s14, s25
	s_addc_u32 s39, s15, 0
	s_add_u32 s14, s14, s4
	s_addc_u32 s15, s15, 0
	v_add_u32_e32 v126, 0x10000, v194
	v_add_u32_e32 v127, 0x10000, v139
	s_add_i32 m0, s22, 0x0
	s_cmp_eq_u32 s23, 0
	global_load_lds_dwordx4 v128, s[12:13]
	s_cbranch_scc1 .Lat_k2_1
	s_add_i32 m0, s22, 0x2000
	s_nop 0
	global_load_lds_dwordx4 v129, s[12:13]
; DEV float max3f(float a, float b, float c) { return fmaxf(fmaxf(a, b), c); }
; #define LOADK(t) do { const long kb_ = KBASE(t); kreg0 = *(const u32x4*)(K + (kb_ + lane) * 1536 + h * 96 + wid * 8); \
;         if (k2) kreg1 = *(const u32x4*)(K + (kb_ + lane) * 1536 + h * 96 + (8 + wid) * 8); } while (0)
; #define LOADV(t) do { const long kb_ = KBASE(t); vreg = *(const u32x4*)(V + (kb_ + 16 * (wid & 3) + (lane >> 2)) * 1024 + h * 64 + (wid >> 2) * 32 + (lane & 3) * 8); } while (0)
; #define STOREK(s) do { LAS unsigned char* st_ = sh + (s) * STG; *(LAS u32x4*)(st_ + wid * 1024 + lane * 16) = kreg0; if (k2) *(LAS u32x4*)(st_ + (8 + wid) * 1024 + lane * 16) = kreg1; } while (0)
; #define STOREV(s) do { LAS unsigned char* st_ = sh + (s) * STG; *(LAS u32x4*)(st_ + KST + wid * 1024 + lane * 16) = vreg; } while (0)
; DEV void attn_unit(int b, int h, int qb, const bf16_t* Q, const bf16_t* K, const bf16_t* V, bf16_t* O, LAS unsigned char* sh, const int tid, const float* qgain) {
;     ...
;     LOADK(0); LOADV(0); STOREK(0); STOREV(0); LOADK(1); STOREK(1); __syncthreads();
;     f32x16 pA0, pA1, pB0 = f32x16{}, pB1 = f32x16{};
;     QKT(pA0, pA1, 0);
;     { float m0 = pA0[0];
; #pragma unroll
;         for (int r = 0; r < 16; ++r) m0 = max3f(m0, pA0[r], pA1[r]);
;         mrun = fmaxf(m0, __shfl_xor(m0, 32)); }
.Lat_k2_1:
	s_add_u32 s12, s12, 0x30000
	s_addc_u32 s13, s13, 0
	s_add_i32 m0, s22, 0x3000
	s_nop 0
	global_load_lds_dwordx4 v145, s[14:15]
	s_add_u32 s14, s14, 0x20000
	s_addc_u32 s15, s15, 0
	s_add_i32 m0, s22, 0x5000
	s_cmp_eq_u32 s23, 0
	global_load_lds_dwordx4 v128, s[12:13]
	s_cbranch_scc1 .Lat_k2_2
	s_add_i32 m0, s22, 0x7000
	s_nop 0
	global_load_lds_dwordx4 v129, s[12:13]
.Lat_k2_2:
	s_add_u32 s12, s12, 0x30000
	s_addc_u32 s13, s13, 0
	s_add_i32 m0, s22, 0x8000
	s_nop 0
	global_load_lds_dwordx4 v145, s[14:15]
	s_add_u32 s14, s14, 0x20000
	s_addc_u32 s15, s15, 0
	s_add_i32 m0, s22, 0x10000
	s_cmp_eq_u32 s23, 0
	global_load_lds_dwordx4 v128, s[12:13]
	s_cbranch_scc1 .Lat_k2_3
	s_add_i32 m0, s22, 0x12000
	s_nop 0
	global_load_lds_dwordx4 v129, s[12:13]
.Lat_k2_3:
	s_add_u32 s12, s12, 0x30000
	s_addc_u32 s13, s13, 0
	v_mov_b32_e32 v0, 0
	v_mov_b32_e32 v1, 0
	v_mov_b32_e32 v2, 0
	v_mov_b32_e32 v3, 0
	v_mov_b32_e32 v4, 0
	v_mov_b32_e32 v5, 0
	v_mov_b32_e32 v6, 0
	v_mov_b32_e32 v7, 0
	v_mov_b32_e32 v8, 0
	v_mov_b32_e32 v9, 0
	v_mov_b32_e32 v10, 0
	v_mov_b32_e32 v11, 0
	v_mov_b32_e32 v12, 0
	v_mov_b32_e32 v13, 0
	v_mov_b32_e32 v14, 0
	v_mov_b32_e32 v15, 0
	v_mov_b32_e32 v16, 0
	v_mov_b32_e32 v17, 0
	v_mov_b32_e32 v18, 0
	v_mov_b32_e32 v19, 0
	v_mov_b32_e32 v20, 0
	v_mov_b32_e32 v21, 0
	v_mov_b32_e32 v22, 0
	v_mov_b32_e32 v23, 0
	v_mov_b32_e32 v24, 0
	v_mov_b32_e32 v25, 0
	v_mov_b32_e32 v26, 0
	v_mov_b32_e32 v27, 0
	v_mov_b32_e32 v28, 0
	v_mov_b32_e32 v29, 0
	v_mov_b32_e32 v30, 0
	v_mov_b32_e32 v31, 0
	v_mov_b32_e32 v147, 0
	s_waitcnt vmcnt(0)
	s_barrier
	ds_read_b128 v[196:199], v194 offset:0
	ds_read_b128 v[200:203], v194 offset:512
	ds_read_b128 v[204:207], v194 offset:2048
	ds_read_b128 v[208:211], v194 offset:2560
	ds_read_b128 v[212:215], v194 offset:4096
	ds_read_b128 v[216:219], v194 offset:4608
	s_waitcnt lgkmcnt(5)
	v_mfma_f32_32x32x16_bf16 v[48:63], v[196:199], v[110:113], 0
	ds_read_b128 v[196:199], v194 offset:6144
	s_waitcnt lgkmcnt(5)
	v_mfma_f32_32x32x16_bf16 v[32:47], v[200:203], v[110:113], 0
	ds_read_b128 v[200:203], v194 offset:6656
	s_waitcnt lgkmcnt(5)
	v_mfma_f32_32x32x16_bf16 v[48:63], v[204:207], v[106:109], v[48:63]
	ds_read_b128 v[204:207], v194 offset:8192
	s_waitcnt lgkmcnt(5)
	v_mfma_f32_32x32x16_bf16 v[32:47], v[208:211], v[106:109], v[32:47]
	ds_read_b128 v[208:211], v194 offset:8704
	s_waitcnt lgkmcnt(5)
	v_mfma_f32_32x32x16_bf16 v[48:63], v[212:215], v[114:117], v[48:63]
	ds_read_b128 v[212:215], v194 offset:10240
	s_waitcnt lgkmcnt(5)
	v_mfma_f32_32x32x16_bf16 v[32:47], v[216:219], v[114:117], v[32:47]
	ds_read_b128 v[216:219], v194 offset:10752
	s_waitcnt lgkmcnt(5)
	v_mfma_f32_32x32x16_bf16 v[48:63], v[196:199], v[118:121], v[48:63]
	s_waitcnt lgkmcnt(4)
	v_mfma_f32_32x32x16_bf16 v[32:47], v[200:203], v[118:121], v[32:47]
	s_waitcnt lgkmcnt(3)
	v_mfma_f32_32x32x16_bf16 v[48:63], v[204:207], v[102:105], v[48:63]
	s_waitcnt lgkmcnt(2)
	v_mfma_f32_32x32x16_bf16 v[32:47], v[208:211], v[102:105], v[32:47]
	s_waitcnt lgkmcnt(1)
	v_mfma_f32_32x32x16_bf16 v[48:63], v[212:215], v[98:101], v[48:63]
	s_waitcnt lgkmcnt(0)
	v_mfma_f32_32x32x16_bf16 v[32:47], v[216:219], v[98:101], v[32:47]
	s_nop 15
	s_nop 3
	v_max_f32_e32 v149, v48, v32
	v_max3_f32 v149, v149, v49, v33
	v_max3_f32 v149, v149, v50, v34
	v_max3_f32 v149, v149, v51, v35
	v_max3_f32 v149, v149, v52, v36
	v_max3_f32 v149, v149, v53, v37
	v_max3_f32 v149, v149, v54, v38
	v_max3_f32 v149, v149, v55, v39
	v_max3_f32 v149, v149, v56, v40
	v_max3_f32 v149, v149, v57, v41
	v_max3_f32 v149, v149, v58, v42
	v_max3_f32 v149, v149, v59, v43
	v_max3_f32 v149, v149, v60, v44
	v_max3_f32 v149, v149, v61, v45
	v_max3_f32 v149, v149, v62, v46
	v_max3_f32 v149, v149, v63, v47
	v_mov_b32_e32 v175, v149
	v_mov_b32_e32 v178, v149
	s_nop 1
	v_permlane32_swap_b32_e32 v175, v178
	v_max_f32_e32 v174, v175, v178
	s_mov_b32 s24, 15
.Lat_loop_4:
	s_add_i32 m0, s22, 0x15000
	s_cmp_eq_u32 s23, 0
	global_load_lds_dwordx4 v128, s[12:13]
	s_cbranch_scc1 .Lat_k2_5
	s_add_i32 m0, s22, 0x17000
	s_nop 0
	global_load_lds_dwordx4 v129, s[12:13]
.Lat_k2_5:
	s_add_u32 s12, s12, 0x30000
	s_addc_u32 s13, s13, 0
	s_add_i32 m0, s22, 0x13000
	s_nop 0
	global_load_lds_dwordx4 v145, s[14:15]
	s_add_u32 s14, s14, 0x20000
	s_addc_u32 s15, s15, 0
	ds_read_b128 v[196:199], v194 offset:20480
	ds_read_b128 v[200:203], v194 offset:20992
	ds_read_b128 v[204:207], v194 offset:22528
	ds_read_b128 v[208:211], v194 offset:23040
	ds_read_b128 v[212:215], v194 offset:24576
	ds_read_b128 v[216:219], v194 offset:25088
	ds_read_b64_tr_b16 v[220:221], v139 offset:0
	ds_read_b64_tr_b16 v[222:223], v139 offset:512
	ds_read_b64_tr_b16 v[228:229], v139 offset:4096
	ds_read_b64_tr_b16 v[230:231], v139 offset:4608
	v_max_f32_e32 v149, v48, v49
	v_sub_f32_e32 v48, v48, v174
	v_sub_f32_e32 v49, v49, v174
	v_exp_f32_e32 v48, v48
	v_exp_f32_e32 v49, v49
	v_mov_b32_e32 v176, v48
	v_mov_b32_e32 v177, v49
	v_cvt_pk_bf16_f32 v48, v48, v49
	v_max3_f32 v149, v149, v50, v51
	v_sub_f32_e32 v50, v50, v174
	v_sub_f32_e32 v51, v51, v174
	v_exp_f32_e32 v50, v50
	s_waitcnt lgkmcnt(9)
	v_mfma_f32_32x32x16_bf16 v[80:95], v[196:199], v[110:113], 0
	ds_read_b128 v[196:199], v194 offset:26624
	ds_read_b64_tr_b16 v[224:225], v139 offset:1024
	ds_read_b64_tr_b16 v[226:227], v139 offset:1536
	v_exp_f32_e32 v51, v51
	v_add_f32_e32 v176, v50, v176
	v_add_f32_e32 v177, v51, v177
	v_cvt_pk_bf16_f32 v49, v50, v51
	v_max3_f32 v149, v149, v52, v53
	v_sub_f32_e32 v52, v52, v174
	v_sub_f32_e32 v53, v53, v174
	s_waitcnt lgkmcnt(11)
	v_mfma_f32_32x32x16_bf16 v[64:79], v[200:203], v[110:113], 0
	ds_read_b128 v[200:203], v194 offset:27136
	ds_read_b64_tr_b16 v[232:233], v139 offset:5120
	ds_read_b64_tr_b16 v[234:235], v139 offset:5632
	v_exp_f32_e32 v52, v52
	v_exp_f32_e32 v53, v53
	v_add_f32_e32 v176, v52, v176
	v_add_f32_e32 v177, v53, v177
	v_cvt_pk_bf16_f32 v50, v52, v53
	v_max3_f32 v149, v149, v54, v55
	v_sub_f32_e32 v54, v54, v174
	s_waitcnt lgkmcnt(13)
	v_mfma_f32_32x32x16_bf16 v[80:95], v[204:207], v[106:109], v[80:95]
	ds_read_b128 v[204:207], v194 offset:28672
	v_sub_f32_e32 v55, v55, v174
	v_exp_f32_e32 v54, v54
	v_exp_f32_e32 v55, v55
	v_add_f32_e32 v176, v54, v176
	v_add_f32_e32 v177, v55, v177
	v_cvt_pk_bf16_f32 v51, v54, v55
	v_max3_f32 v149, v149, v56, v57
	s_waitcnt lgkmcnt(13)
	v_mfma_f32_32x32x16_bf16 v[64:79], v[208:211], v[106:109], v[64:79]
	ds_read_b128 v[208:211], v194 offset:29184
	v_sub_f32_e32 v56, v56, v174
	v_sub_f32_e32 v57, v57, v174
	v_exp_f32_e32 v56, v56
	v_exp_f32_e32 v57, v57
	v_add_f32_e32 v176, v56, v176
	v_add_f32_e32 v177, v57, v177
	v_cvt_pk_bf16_f32 v52, v56, v57
	s_waitcnt lgkmcnt(13)
	v_mfma_f32_32x32x16_bf16 v[80:95], v[212:215], v[114:117], v[80:95]
	ds_read_b128 v[212:215], v194 offset:30720
	v_max3_f32 v149, v149, v58, v59
	v_sub_f32_e32 v58, v58, v174
	v_sub_f32_e32 v59, v59, v174
	v_exp_f32_e32 v58, v58
	v_exp_f32_e32 v59, v59
	v_add_f32_e32 v176, v58, v176
	v_add_f32_e32 v177, v59, v177
	s_waitcnt lgkmcnt(11)
	v_mfma_f32_32x32x16_bf16 v[0:15], v[48:51], v[220:223], v[0:15]
	ds_read_b64_tr_b16 v[236:237], v139 offset:2048
	ds_read_b64_tr_b16 v[238:239], v139 offset:2560
	v_cvt_pk_bf16_f32 v53, v58, v59
	v_max3_f32 v149, v149, v60, v61
	v_sub_f32_e32 v60, v60, v174
	v_sub_f32_e32 v61, v61, v174
	v_exp_f32_e32 v60, v60
	v_exp_f32_e32 v61, v61
	v_add_f32_e32 v176, v60, v176
	s_waitcnt lgkmcnt(11)
	v_mfma_f32_32x32x16_bf16 v[16:31], v[48:51], v[228:231], v[16:31]
	ds_read_b64_tr_b16 v[244:245], v139 offset:6144
	ds_read_b64_tr_b16 v[246:247], v139 offset:6656
	v_add_f32_e32 v177, v61, v177
	v_cvt_pk_bf16_f32 v54, v60, v61
	v_max3_f32 v149, v149, v62, v63
	v_sub_f32_e32 v62, v62, v174
	v_sub_f32_e32 v63, v63, v174
	v_exp_f32_e32 v62, v62
	v_exp_f32_e32 v63, v63
	v_mfma_f32_32x32x16_bf16 v[64:79], v[216:219], v[114:117], v[64:79]
	ds_read_b128 v[216:219], v194 offset:31232
	v_add_f32_e32 v176, v62, v176
	v_add_f32_e32 v177, v63, v177
	v_cvt_pk_bf16_f32 v55, v62, v63
	v_max3_f32 v149, v149, v32, v33
	v_sub_f32_e32 v32, v32, v174
	v_sub_f32_e32 v33, v33, v174
	v_exp_f32_e32 v32, v32
	s_waitcnt lgkmcnt(13)
	v_mfma_f32_32x32x16_bf16 v[80:95], v[196:199], v[118:121], v[80:95]
	v_exp_f32_e32 v33, v33
	v_add_f32_e32 v176, v32, v176
	v_add_f32_e32 v177, v33, v177
	v_cvt_pk_bf16_f32 v32, v32, v33
	v_max3_f32 v149, v149, v34, v35
	v_sub_f32_e32 v34, v34, v174
	v_sub_f32_e32 v35, v35, v174
	s_waitcnt lgkmcnt(10)
	v_mfma_f32_32x32x16_bf16 v[64:79], v[200:203], v[118:121], v[64:79]
	v_exp_f32_e32 v34, v34
	v_exp_f32_e32 v35, v35
	v_add_f32_e32 v176, v34, v176
	v_add_f32_e32 v177, v35, v177
	v_cvt_pk_bf16_f32 v33, v34, v35
	v_max3_f32 v149, v149, v36, v37
	v_sub_f32_e32 v36, v36, v174
	v_mfma_f32_32x32x16_bf16 v[0:15], v[52:55], v[224:227], v[0:15]
	ds_read_b64_tr_b16 v[240:241], v139 offset:3072
	ds_read_b64_tr_b16 v[242:243], v139 offset:3584
	v_sub_f32_e32 v37, v37, v174
	v_exp_f32_e32 v36, v36
	v_exp_f32_e32 v37, v37
	v_add_f32_e32 v176, v36, v176
	v_add_f32_e32 v177, v37, v177
	v_cvt_pk_bf16_f32 v34, v36, v37
	v_max3_f32 v149, v149, v38, v39
	s_waitcnt lgkmcnt(10)
	v_mfma_f32_32x32x16_bf16 v[16:31], v[52:55], v[232:235], v[16:31]
	ds_read_b64_tr_b16 v[122:123], v139 offset:7168
	ds_read_b64_tr_b16 v[124:125], v139 offset:7680
	v_sub_f32_e32 v38, v38, v174
	v_sub_f32_e32 v39, v39, v174
	v_exp_f32_e32 v38, v38
	v_exp_f32_e32 v39, v39
	v_add_f32_e32 v176, v38, v176
	v_add_f32_e32 v177, v39, v177
	v_cvt_pk_bf16_f32 v35, v38, v39
	s_waitcnt lgkmcnt(11)
	v_mfma_f32_32x32x16_bf16 v[80:95], v[204:207], v[102:105], v[80:95]
	v_max3_f32 v149, v149, v40, v41
	v_sub_f32_e32 v40, v40, v174
	v_sub_f32_e32 v41, v41, v174
	v_exp_f32_e32 v40, v40
	v_exp_f32_e32 v41, v41
	v_add_f32_e32 v176, v40, v176
	v_add_f32_e32 v177, v41, v177
	s_waitcnt lgkmcnt(10)
	v_mfma_f32_32x32x16_bf16 v[64:79], v[208:211], v[102:105], v[64:79]
	v_cvt_pk_bf16_f32 v36, v40, v41
	v_max3_f32 v149, v149, v42, v43
	v_sub_f32_e32 v42, v42, v174
	v_sub_f32_e32 v43, v43, v174
	v_exp_f32_e32 v42, v42
	v_exp_f32_e32 v43, v43
	v_add_f32_e32 v176, v42, v176
	s_waitcnt lgkmcnt(7)
	v_mfma_f32_32x32x16_bf16 v[0:15], v[32:35], v[236:239], v[0:15]
	v_add_f32_e32 v177, v43, v177
	v_cvt_pk_bf16_f32 v37, v42, v43
	v_max3_f32 v149, v149, v44, v45
	v_sub_f32_e32 v44, v44, v174
	v_sub_f32_e32 v45, v45, v174
	v_exp_f32_e32 v44, v44
	v_exp_f32_e32 v45, v45
	s_waitcnt lgkmcnt(5)
	v_mfma_f32_32x32x16_bf16 v[16:31], v[32:35], v[244:247], v[16:31]
	v_add_f32_e32 v176, v44, v176
	v_add_f32_e32 v177, v45, v177
	v_cvt_pk_bf16_f32 v38, v44, v45
	v_max3_f32 v149, v149, v46, v47
	v_sub_f32_e32 v46, v46, v174
	v_sub_f32_e32 v47, v47, v174
	v_exp_f32_e32 v46, v46
	v_mfma_f32_32x32x16_bf16 v[80:95], v[212:215], v[98:101], v[80:95]
	v_exp_f32_e32 v47, v47
	v_add_f32_e32 v176, v46, v176
	v_add_f32_e32 v177, v47, v177
	v_cvt_pk_bf16_f32 v39, v46, v47
	v_add_f32_e32 v179, v176, v177
	v_mov_b32_e32 v175, v149
	v_mov_b32_e32 v178, v149
	s_waitcnt lgkmcnt(4)
	v_mfma_f32_32x32x16_bf16 v[64:79], v[216:219], v[98:101], v[64:79]
	v_add_f32_e32 v147, v147, v179
	s_nop 1
	v_permlane32_swap_b32_e32 v175, v178
	v_max_f32_e32 v175, v175, v178
	v_sub_f32_e32 v175, v175, v174
	v_cmp_lt_f32_e32 vcc, s43, v175
	s_waitcnt lgkmcnt(2)
	v_mfma_f32_32x32x16_bf16 v[0:15], v[36:39], v[240:243], v[0:15]
	s_waitcnt lgkmcnt(0)
	v_mfma_f32_32x32x16_bf16 v[16:31], v[36:39], v[122:125], v[16:31]
	s_cbranch_vccz .Lat_nr_6
	v_max_f32_e32 v175, v175, v175
	v_max_f32_e32 v175, 0, v175
	v_exp_f32_e64 v178, -v175
	s_and_saveexec_b64 s[4:5], s[2:3]
	ds_write_b32 v143, v178 offset:40960
	s_or_b64 exec, exec, s[4:5]
	s_waitcnt lgkmcnt(0)
	v_add_u32_e32 v179, s33, v191
	v_add_f32_e32 v174, v174, v175
	v_mul_f32_e32 v147, v147, v178
	ds_read_b128 v[196:199], v179 offset:40960
	ds_read_b128 v[200:203], v179 offset:40992
	ds_read_b128 v[204:207], v179 offset:41024
	ds_read_b128 v[208:211], v179 offset:41056
	s_waitcnt lgkmcnt(0)
	s_nop 15
	v_pk_mul_f32 v[0:1], v[0:1], v[196:197]
	v_pk_mul_f32 v[2:3], v[2:3], v[198:199]
	v_pk_mul_f32 v[4:5], v[4:5], v[200:201]
	v_pk_mul_f32 v[6:7], v[6:7], v[202:203]
	v_pk_mul_f32 v[8:9], v[8:9], v[204:205]
	v_pk_mul_f32 v[10:11], v[10:11], v[206:207]
	v_pk_mul_f32 v[12:13], v[12:13], v[208:209]
	v_pk_mul_f32 v[14:15], v[14:15], v[210:211]
	v_pk_mul_f32 v[16:17], v[16:17], v[196:197]
	v_pk_mul_f32 v[18:19], v[18:19], v[198:199]
	v_pk_mul_f32 v[20:21], v[20:21], v[200:201]
	v_pk_mul_f32 v[22:23], v[22:23], v[202:203]
	v_pk_mul_f32 v[24:25], v[24:25], v[204:205]
	v_pk_mul_f32 v[26:27], v[26:27], v[206:207]
	v_pk_mul_f32 v[28:29], v[28:29], v[208:209]
	v_pk_mul_f32 v[30:31], v[30:31], v[210:211]
.Lat_nr_6:
	s_waitcnt vmcnt(2)
	s_barrier
	s_add_i32 m0, s22, 0x0
	s_cmp_eq_u32 s23, 0
	global_load_lds_dwordx4 v128, s[12:13]
	s_cbranch_scc1 .Lat_k2_7
	s_add_i32 m0, s22, 0x2000
	s_nop 0
	global_load_lds_dwordx4 v129, s[12:13]
.Lat_k2_7:
	s_add_u32 s12, s12, 0x30000
	s_addc_u32 s13, s13, 0
	s_add_i32 m0, s22, 0x18000
	s_nop 0
	global_load_lds_dwordx4 v145, s[14:15]
	s_add_u32 s14, s14, 0x20000
	s_addc_u32 s15, s15, 0
	ds_read_b128 v[196:199], v126 offset:0
	ds_read_b128 v[200:203], v126 offset:512
	ds_read_b128 v[204:207], v126 offset:2048
	ds_read_b128 v[208:211], v126 offset:2560
	ds_read_b128 v[212:215], v126 offset:4096
	ds_read_b128 v[216:219], v126 offset:4608
	ds_read_b64_tr_b16 v[220:221], v139 offset:20480
	ds_read_b64_tr_b16 v[222:223], v139 offset:20992
	ds_read_b64_tr_b16 v[228:229], v139 offset:24576
	ds_read_b64_tr_b16 v[230:231], v139 offset:25088
	v_max_f32_e32 v149, v80, v81
	v_sub_f32_e32 v80, v80, v174
	v_sub_f32_e32 v81, v81, v174
	v_exp_f32_e32 v80, v80
	v_exp_f32_e32 v81, v81
	v_mov_b32_e32 v176, v80
	v_mov_b32_e32 v177, v81
	v_cvt_pk_bf16_f32 v80, v80, v81
	v_max3_f32 v149, v149, v82, v83
	v_sub_f32_e32 v82, v82, v174
	v_sub_f32_e32 v83, v83, v174
	v_exp_f32_e32 v82, v82
	s_waitcnt lgkmcnt(9)
	v_mfma_f32_32x32x16_bf16 v[48:63], v[196:199], v[110:113], 0
	ds_read_b128 v[196:199], v126 offset:6144
	ds_read_b64_tr_b16 v[224:225], v139 offset:21504
	ds_read_b64_tr_b16 v[226:227], v139 offset:22016
	v_exp_f32_e32 v83, v83
	v_add_f32_e32 v176, v82, v176
	v_add_f32_e32 v177, v83, v177
	v_cvt_pk_bf16_f32 v81, v82, v83
	v_max3_f32 v149, v149, v84, v85
	v_sub_f32_e32 v84, v84, v174
	v_sub_f32_e32 v85, v85, v174
	s_waitcnt lgkmcnt(11)
	v_mfma_f32_32x32x16_bf16 v[32:47], v[200:203], v[110:113], 0
	ds_read_b128 v[200:203], v126 offset:6656
	ds_read_b64_tr_b16 v[232:233], v139 offset:25600
	ds_read_b64_tr_b16 v[234:235], v139 offset:26112
	v_exp_f32_e32 v84, v84
	v_exp_f32_e32 v85, v85
	v_add_f32_e32 v176, v84, v176
	v_add_f32_e32 v177, v85, v177
	v_cvt_pk_bf16_f32 v82, v84, v85
	v_max3_f32 v149, v149, v86, v87
	v_sub_f32_e32 v86, v86, v174
	s_waitcnt lgkmcnt(13)
	v_mfma_f32_32x32x16_bf16 v[48:63], v[204:207], v[106:109], v[48:63]
	ds_read_b128 v[204:207], v126 offset:8192
	v_sub_f32_e32 v87, v87, v174
	v_exp_f32_e32 v86, v86
	v_exp_f32_e32 v87, v87
	v_add_f32_e32 v176, v86, v176
	v_add_f32_e32 v177, v87, v177
	v_cvt_pk_bf16_f32 v83, v86, v87
	v_max3_f32 v149, v149, v88, v89
	s_waitcnt lgkmcnt(13)
	v_mfma_f32_32x32x16_bf16 v[32:47], v[208:211], v[106:109], v[32:47]
	ds_read_b128 v[208:211], v126 offset:8704
	v_sub_f32_e32 v88, v88, v174
	v_sub_f32_e32 v89, v89, v174
	v_exp_f32_e32 v88, v88
	v_exp_f32_e32 v89, v89
	v_add_f32_e32 v176, v88, v176
	v_add_f32_e32 v177, v89, v177
	v_cvt_pk_bf16_f32 v84, v88, v89
	s_waitcnt lgkmcnt(13)
	v_mfma_f32_32x32x16_bf16 v[48:63], v[212:215], v[114:117], v[48:63]
	ds_read_b128 v[212:215], v126 offset:10240
	v_max3_f32 v149, v149, v90, v91
	v_sub_f32_e32 v90, v90, v174
	v_sub_f32_e32 v91, v91, v174
	v_exp_f32_e32 v90, v90
	v_exp_f32_e32 v91, v91
	v_add_f32_e32 v176, v90, v176
	v_add_f32_e32 v177, v91, v177
	s_waitcnt lgkmcnt(11)
	v_mfma_f32_32x32x16_bf16 v[0:15], v[80:83], v[220:223], v[0:15]
	ds_read_b64_tr_b16 v[236:237], v139 offset:22528
	ds_read_b64_tr_b16 v[238:239], v139 offset:23040
	v_cvt_pk_bf16_f32 v85, v90, v91
	v_max3_f32 v149, v149, v92, v93
	v_sub_f32_e32 v92, v92, v174
	v_sub_f32_e32 v93, v93, v174
	v_exp_f32_e32 v92, v92
	v_exp_f32_e32 v93, v93
	v_add_f32_e32 v176, v92, v176
	s_waitcnt lgkmcnt(11)
	v_mfma_f32_32x32x16_bf16 v[16:31], v[80:83], v[228:231], v[16:31]
	ds_read_b64_tr_b16 v[244:245], v139 offset:26624
	ds_read_b64_tr_b16 v[246:247], v139 offset:27136
	v_add_f32_e32 v177, v93, v177
	v_cvt_pk_bf16_f32 v86, v92, v93
	v_max3_f32 v149, v149, v94, v95
	v_sub_f32_e32 v94, v94, v174
	v_sub_f32_e32 v95, v95, v174
	v_exp_f32_e32 v94, v94
	v_exp_f32_e32 v95, v95
	v_mfma_f32_32x32x16_bf16 v[32:47], v[216:219], v[114:117], v[32:47]
	ds_read_b128 v[216:219], v126 offset:10752
	v_add_f32_e32 v176, v94, v176
	v_add_f32_e32 v177, v95, v177
	v_cvt_pk_bf16_f32 v87, v94, v95
	v_max3_f32 v149, v149, v64, v65
	v_sub_f32_e32 v64, v64, v174
	v_sub_f32_e32 v65, v65, v174
	v_exp_f32_e32 v64, v64
	s_waitcnt lgkmcnt(13)
	v_mfma_f32_32x32x16_bf16 v[48:63], v[196:199], v[118:121], v[48:63]
	v_exp_f32_e32 v65, v65
	v_add_f32_e32 v176, v64, v176
	v_add_f32_e32 v177, v65, v177
	v_cvt_pk_bf16_f32 v64, v64, v65
	v_max3_f32 v149, v149, v66, v67
	v_sub_f32_e32 v66, v66, v174
	v_sub_f32_e32 v67, v67, v174
	s_waitcnt lgkmcnt(10)
	v_mfma_f32_32x32x16_bf16 v[32:47], v[200:203], v[118:121], v[32:47]
	v_exp_f32_e32 v66, v66
	v_exp_f32_e32 v67, v67
	v_add_f32_e32 v176, v66, v176
	v_add_f32_e32 v177, v67, v177
	v_cvt_pk_bf16_f32 v65, v66, v67
	v_max3_f32 v149, v149, v68, v69
	v_sub_f32_e32 v68, v68, v174
	v_mfma_f32_32x32x16_bf16 v[0:15], v[84:87], v[224:227], v[0:15]
	ds_read_b64_tr_b16 v[240:241], v139 offset:23552
	ds_read_b64_tr_b16 v[242:243], v139 offset:24064
	v_sub_f32_e32 v69, v69, v174
	v_exp_f32_e32 v68, v68
	v_exp_f32_e32 v69, v69
	v_add_f32_e32 v176, v68, v176
	v_add_f32_e32 v177, v69, v177
	v_cvt_pk_bf16_f32 v66, v68, v69
	v_max3_f32 v149, v149, v70, v71
	s_waitcnt lgkmcnt(10)
	v_mfma_f32_32x32x16_bf16 v[16:31], v[84:87], v[232:235], v[16:31]
	ds_read_b64_tr_b16 v[122:123], v139 offset:27648
	ds_read_b64_tr_b16 v[124:125], v139 offset:28160
	v_sub_f32_e32 v70, v70, v174
	v_sub_f32_e32 v71, v71, v174
	v_exp_f32_e32 v70, v70
	v_exp_f32_e32 v71, v71
	v_add_f32_e32 v176, v70, v176
	v_add_f32_e32 v177, v71, v177
	v_cvt_pk_bf16_f32 v67, v70, v71
	s_waitcnt lgkmcnt(11)
	v_mfma_f32_32x32x16_bf16 v[48:63], v[204:207], v[102:105], v[48:63]
	v_max3_f32 v149, v149, v72, v73
	v_sub_f32_e32 v72, v72, v174
	v_sub_f32_e32 v73, v73, v174
	v_exp_f32_e32 v72, v72
	v_exp_f32_e32 v73, v73
	v_add_f32_e32 v176, v72, v176
	v_add_f32_e32 v177, v73, v177
	s_waitcnt lgkmcnt(10)
	v_mfma_f32_32x32x16_bf16 v[32:47], v[208:211], v[102:105], v[32:47]
	v_cvt_pk_bf16_f32 v68, v72, v73
	v_max3_f32 v149, v149, v74, v75
	v_sub_f32_e32 v74, v74, v174
	v_sub_f32_e32 v75, v75, v174
	v_exp_f32_e32 v74, v74
	v_exp_f32_e32 v75, v75
	v_add_f32_e32 v176, v74, v176
	s_waitcnt lgkmcnt(7)
	v_mfma_f32_32x32x16_bf16 v[0:15], v[64:67], v[236:239], v[0:15]
	v_add_f32_e32 v177, v75, v177
	v_cvt_pk_bf16_f32 v69, v74, v75
	v_max3_f32 v149, v149, v76, v77
	v_sub_f32_e32 v76, v76, v174
	v_sub_f32_e32 v77, v77, v174
	v_exp_f32_e32 v76, v76
	v_exp_f32_e32 v77, v77
	s_waitcnt lgkmcnt(5)
	v_mfma_f32_32x32x16_bf16 v[16:31], v[64:67], v[244:247], v[16:31]
	v_add_f32_e32 v176, v76, v176
	v_add_f32_e32 v177, v77, v177
	v_cvt_pk_bf16_f32 v70, v76, v77
	v_max3_f32 v149, v149, v78, v79
	v_sub_f32_e32 v78, v78, v174
	v_sub_f32_e32 v79, v79, v174
	v_exp_f32_e32 v78, v78
	v_mfma_f32_32x32x16_bf16 v[48:63], v[212:215], v[98:101], v[48:63]
	v_exp_f32_e32 v79, v79
	v_add_f32_e32 v176, v78, v176
	v_add_f32_e32 v177, v79, v177
	v_cvt_pk_bf16_f32 v71, v78, v79
	v_add_f32_e32 v179, v176, v177
	v_mov_b32_e32 v175, v149
	v_mov_b32_e32 v178, v149
	s_waitcnt lgkmcnt(4)
	v_mfma_f32_32x32x16_bf16 v[32:47], v[216:219], v[98:101], v[32:47]
	v_add_f32_e32 v147, v147, v179
	s_nop 1
	v_permlane32_swap_b32_e32 v175, v178
	v_max_f32_e32 v175, v175, v178
	v_sub_f32_e32 v175, v175, v174
	v_cmp_lt_f32_e32 vcc, s43, v175
	s_waitcnt lgkmcnt(2)
	v_mfma_f32_32x32x16_bf16 v[0:15], v[68:71], v[240:243], v[0:15]
	s_waitcnt lgkmcnt(0)
	v_mfma_f32_32x32x16_bf16 v[16:31], v[68:71], v[122:125], v[16:31]
	s_cbranch_vccz .Lat_nr_8
	v_max_f32_e32 v175, v175, v175
	v_max_f32_e32 v175, 0, v175
	v_exp_f32_e64 v178, -v175
	s_and_saveexec_b64 s[4:5], s[2:3]
	ds_write_b32 v143, v178 offset:40960
	s_or_b64 exec, exec, s[4:5]
	s_waitcnt lgkmcnt(0)
	v_add_u32_e32 v179, s33, v191
	v_add_f32_e32 v174, v174, v175
	v_mul_f32_e32 v147, v147, v178
	ds_read_b128 v[196:199], v179 offset:40960
	ds_read_b128 v[200:203], v179 offset:40992
	ds_read_b128 v[204:207], v179 offset:41024
	ds_read_b128 v[208:211], v179 offset:41056
	s_waitcnt lgkmcnt(0)
	s_nop 15
	v_pk_mul_f32 v[0:1], v[0:1], v[196:197]
	v_pk_mul_f32 v[2:3], v[2:3], v[198:199]
	v_pk_mul_f32 v[4:5], v[4:5], v[200:201]
	v_pk_mul_f32 v[6:7], v[6:7], v[202:203]
	v_pk_mul_f32 v[8:9], v[8:9], v[204:205]
	v_pk_mul_f32 v[10:11], v[10:11], v[206:207]
	v_pk_mul_f32 v[12:13], v[12:13], v[208:209]
	v_pk_mul_f32 v[14:15], v[14:15], v[210:211]
	v_pk_mul_f32 v[16:17], v[16:17], v[196:197]
	v_pk_mul_f32 v[18:19], v[18:19], v[198:199]
	v_pk_mul_f32 v[20:21], v[20:21], v[200:201]
	v_pk_mul_f32 v[22:23], v[22:23], v[202:203]
	v_pk_mul_f32 v[24:25], v[24:25], v[204:205]
	v_pk_mul_f32 v[26:27], v[26:27], v[206:207]
	v_pk_mul_f32 v[28:29], v[28:29], v[208:209]
	v_pk_mul_f32 v[30:31], v[30:31], v[210:211]
.Lat_nr_8:
	s_waitcnt vmcnt(2)
	s_barrier
	s_add_i32 m0, s22, 0x5000
	s_cmp_eq_u32 s23, 0
	global_load_lds_dwordx4 v128, s[12:13]
	s_cbranch_scc1 .Lat_k2_9
	s_add_i32 m0, s22, 0x7000
	s_nop 0
	global_load_lds_dwordx4 v129, s[12:13]
.Lat_k2_9:
	s_add_u32 s12, s12, 0x30000
	s_addc_u32 s13, s13, 0
	s_add_i32 m0, s22, 0x3000
	s_nop 0
	global_load_lds_dwordx4 v145, s[14:15]
	s_add_u32 s14, s14, 0x20000
	s_addc_u32 s15, s15, 0
	ds_read_b128 v[196:199], v126 offset:20480
	ds_read_b128 v[200:203], v126 offset:20992
	ds_read_b128 v[204:207], v126 offset:22528
	ds_read_b128 v[208:211], v126 offset:23040
	ds_read_b128 v[212:215], v126 offset:24576
	ds_read_b128 v[216:219], v126 offset:25088
	ds_read_b64_tr_b16 v[220:221], v127 offset:0
	ds_read_b64_tr_b16 v[222:223], v127 offset:512
	ds_read_b64_tr_b16 v[228:229], v127 offset:4096
	ds_read_b64_tr_b16 v[230:231], v127 offset:4608
	v_max_f32_e32 v149, v48, v49
	v_sub_f32_e32 v48, v48, v174
	v_sub_f32_e32 v49, v49, v174
	v_exp_f32_e32 v48, v48
	v_exp_f32_e32 v49, v49
	v_mov_b32_e32 v176, v48
	v_mov_b32_e32 v177, v49
	v_cvt_pk_bf16_f32 v48, v48, v49
	v_max3_f32 v149, v149, v50, v51
	v_sub_f32_e32 v50, v50, v174
	v_sub_f32_e32 v51, v51, v174
	v_exp_f32_e32 v50, v50
	s_waitcnt lgkmcnt(9)
	v_mfma_f32_32x32x16_bf16 v[80:95], v[196:199], v[110:113], 0
	ds_read_b128 v[196:199], v126 offset:26624
	ds_read_b64_tr_b16 v[224:225], v127 offset:1024
	ds_read_b64_tr_b16 v[226:227], v127 offset:1536
	v_exp_f32_e32 v51, v51
	v_add_f32_e32 v176, v50, v176
	v_add_f32_e32 v177, v51, v177
	v_cvt_pk_bf16_f32 v49, v50, v51
	v_max3_f32 v149, v149, v52, v53
	v_sub_f32_e32 v52, v52, v174
	v_sub_f32_e32 v53, v53, v174
	s_waitcnt lgkmcnt(11)
	v_mfma_f32_32x32x16_bf16 v[64:79], v[200:203], v[110:113], 0
	ds_read_b128 v[200:203], v126 offset:27136
	ds_read_b64_tr_b16 v[232:233], v127 offset:5120
	ds_read_b64_tr_b16 v[234:235], v127 offset:5632
	v_exp_f32_e32 v52, v52
	v_exp_f32_e32 v53, v53
	v_add_f32_e32 v176, v52, v176
	v_add_f32_e32 v177, v53, v177
	v_cvt_pk_bf16_f32 v50, v52, v53
	v_max3_f32 v149, v149, v54, v55
	v_sub_f32_e32 v54, v54, v174
	s_waitcnt lgkmcnt(13)
	v_mfma_f32_32x32x16_bf16 v[80:95], v[204:207], v[106:109], v[80:95]
	ds_read_b128 v[204:207], v126 offset:28672
	v_sub_f32_e32 v55, v55, v174
	v_exp_f32_e32 v54, v54
	v_exp_f32_e32 v55, v55
	v_add_f32_e32 v176, v54, v176
	v_add_f32_e32 v177, v55, v177
	v_cvt_pk_bf16_f32 v51, v54, v55
	v_max3_f32 v149, v149, v56, v57
	s_waitcnt lgkmcnt(13)
	v_mfma_f32_32x32x16_bf16 v[64:79], v[208:211], v[106:109], v[64:79]
	ds_read_b128 v[208:211], v126 offset:29184
	v_sub_f32_e32 v56, v56, v174
	v_sub_f32_e32 v57, v57, v174
	v_exp_f32_e32 v56, v56
	v_exp_f32_e32 v57, v57
	v_add_f32_e32 v176, v56, v176
	v_add_f32_e32 v177, v57, v177
	v_cvt_pk_bf16_f32 v52, v56, v57
	s_waitcnt lgkmcnt(13)
	v_mfma_f32_32x32x16_bf16 v[80:95], v[212:215], v[114:117], v[80:95]
	ds_read_b128 v[212:215], v126 offset:30720
	v_max3_f32 v149, v149, v58, v59
	v_sub_f32_e32 v58, v58, v174
	v_sub_f32_e32 v59, v59, v174
	v_exp_f32_e32 v58, v58
	v_exp_f32_e32 v59, v59
	v_add_f32_e32 v176, v58, v176
	v_add_f32_e32 v177, v59, v177
	s_waitcnt lgkmcnt(11)
	v_mfma_f32_32x32x16_bf16 v[0:15], v[48:51], v[220:223], v[0:15]
	ds_read_b64_tr_b16 v[236:237], v127 offset:2048
	ds_read_b64_tr_b16 v[238:239], v127 offset:2560
	v_cvt_pk_bf16_f32 v53, v58, v59
	v_max3_f32 v149, v149, v60, v61
	v_sub_f32_e32 v60, v60, v174
	v_sub_f32_e32 v61, v61, v174
	v_exp_f32_e32 v60, v60
	v_exp_f32_e32 v61, v61
	v_add_f32_e32 v176, v60, v176
	s_waitcnt lgkmcnt(11)
	v_mfma_f32_32x32x16_bf16 v[16:31], v[48:51], v[228:231], v[16:31]
	ds_read_b64_tr_b16 v[244:245], v127 offset:6144
	ds_read_b64_tr_b16 v[246:247], v127 offset:6656
	v_add_f32_e32 v177, v61, v177
	v_cvt_pk_bf16_f32 v54, v60, v61
	v_max3_f32 v149, v149, v62, v63
	v_sub_f32_e32 v62, v62, v174
	v_sub_f32_e32 v63, v63, v174
	v_exp_f32_e32 v62, v62
	v_exp_f32_e32 v63, v63
	v_mfma_f32_32x32x16_bf16 v[64:79], v[216:219], v[114:117], v[64:79]
	ds_read_b128 v[216:219], v126 offset:31232
	v_add_f32_e32 v176, v62, v176
	v_add_f32_e32 v177, v63, v177
	v_cvt_pk_bf16_f32 v55, v62, v63
	v_max3_f32 v149, v149, v32, v33
	v_sub_f32_e32 v32, v32, v174
	v_sub_f32_e32 v33, v33, v174
	v_exp_f32_e32 v32, v32
	s_waitcnt lgkmcnt(13)
	v_mfma_f32_32x32x16_bf16 v[80:95], v[196:199], v[118:121], v[80:95]
	v_exp_f32_e32 v33, v33
	v_add_f32_e32 v176, v32, v176
	v_add_f32_e32 v177, v33, v177
	v_cvt_pk_bf16_f32 v32, v32, v33
	v_max3_f32 v149, v149, v34, v35
	v_sub_f32_e32 v34, v34, v174
	v_sub_f32_e32 v35, v35, v174
	s_waitcnt lgkmcnt(10)
	v_mfma_f32_32x32x16_bf16 v[64:79], v[200:203], v[118:121], v[64:79]
	v_exp_f32_e32 v34, v34
	v_exp_f32_e32 v35, v35
	v_add_f32_e32 v176, v34, v176
	v_add_f32_e32 v177, v35, v177
	v_cvt_pk_bf16_f32 v33, v34, v35
	v_max3_f32 v149, v149, v36, v37
	v_sub_f32_e32 v36, v36, v174
	v_mfma_f32_32x32x16_bf16 v[0:15], v[52:55], v[224:227], v[0:15]
	ds_read_b64_tr_b16 v[240:241], v127 offset:3072
	ds_read_b64_tr_b16 v[242:243], v127 offset:3584
	v_sub_f32_e32 v37, v37, v174
	v_exp_f32_e32 v36, v36
	v_exp_f32_e32 v37, v37
	v_add_f32_e32 v176, v36, v176
	v_add_f32_e32 v177, v37, v177
	v_cvt_pk_bf16_f32 v34, v36, v37
	v_max3_f32 v149, v149, v38, v39
	s_waitcnt lgkmcnt(10)
	v_mfma_f32_32x32x16_bf16 v[16:31], v[52:55], v[232:235], v[16:31]
	ds_read_b64_tr_b16 v[122:123], v127 offset:7168
	ds_read_b64_tr_b16 v[124:125], v127 offset:7680
	v_sub_f32_e32 v38, v38, v174
	v_sub_f32_e32 v39, v39, v174
	v_exp_f32_e32 v38, v38
	v_exp_f32_e32 v39, v39
	v_add_f32_e32 v176, v38, v176
	v_add_f32_e32 v177, v39, v177
	v_cvt_pk_bf16_f32 v35, v38, v39
	s_waitcnt lgkmcnt(11)
	v_mfma_f32_32x32x16_bf16 v[80:95], v[204:207], v[102:105], v[80:95]
	v_max3_f32 v149, v149, v40, v41
	v_sub_f32_e32 v40, v40, v174
	v_sub_f32_e32 v41, v41, v174
	v_exp_f32_e32 v40, v40
	v_exp_f32_e32 v41, v41
	v_add_f32_e32 v176, v40, v176
	v_add_f32_e32 v177, v41, v177
	s_waitcnt lgkmcnt(10)
	v_mfma_f32_32x32x16_bf16 v[64:79], v[208:211], v[102:105], v[64:79]
	v_cvt_pk_bf16_f32 v36, v40, v41
	v_max3_f32 v149, v149, v42, v43
	v_sub_f32_e32 v42, v42, v174
	v_sub_f32_e32 v43, v43, v174
	v_exp_f32_e32 v42, v42
	v_exp_f32_e32 v43, v43
	v_add_f32_e32 v176, v42, v176
	s_waitcnt lgkmcnt(7)
	v_mfma_f32_32x32x16_bf16 v[0:15], v[32:35], v[236:239], v[0:15]
	v_add_f32_e32 v177, v43, v177
	v_cvt_pk_bf16_f32 v37, v42, v43
	v_max3_f32 v149, v149, v44, v45
	v_sub_f32_e32 v44, v44, v174
	v_sub_f32_e32 v45, v45, v174
	v_exp_f32_e32 v44, v44
	v_exp_f32_e32 v45, v45
	s_waitcnt lgkmcnt(5)
	v_mfma_f32_32x32x16_bf16 v[16:31], v[32:35], v[244:247], v[16:31]
	v_add_f32_e32 v176, v44, v176
	v_add_f32_e32 v177, v45, v177
	v_cvt_pk_bf16_f32 v38, v44, v45
	v_max3_f32 v149, v149, v46, v47
	v_sub_f32_e32 v46, v46, v174
	v_sub_f32_e32 v47, v47, v174
	v_exp_f32_e32 v46, v46
	v_mfma_f32_32x32x16_bf16 v[80:95], v[212:215], v[98:101], v[80:95]
	v_exp_f32_e32 v47, v47
	v_add_f32_e32 v176, v46, v176
	v_add_f32_e32 v177, v47, v177
	v_cvt_pk_bf16_f32 v39, v46, v47
	v_add_f32_e32 v179, v176, v177
	v_mov_b32_e32 v175, v149
	v_mov_b32_e32 v178, v149
	s_waitcnt lgkmcnt(4)
	v_mfma_f32_32x32x16_bf16 v[64:79], v[216:219], v[98:101], v[64:79]
	v_add_f32_e32 v147, v147, v179
	s_nop 1
	v_permlane32_swap_b32_e32 v175, v178
	v_max_f32_e32 v175, v175, v178
	v_sub_f32_e32 v175, v175, v174
	v_cmp_lt_f32_e32 vcc, s43, v175
	s_waitcnt lgkmcnt(2)
	v_mfma_f32_32x32x16_bf16 v[0:15], v[36:39], v[240:243], v[0:15]
	s_waitcnt lgkmcnt(0)
	v_mfma_f32_32x32x16_bf16 v[16:31], v[36:39], v[122:125], v[16:31]
	s_cbranch_vccz .Lat_nr_10
	v_max_f32_e32 v175, v175, v175
	v_max_f32_e32 v175, 0, v175
	v_exp_f32_e64 v178, -v175
	s_and_saveexec_b64 s[4:5], s[2:3]
	ds_write_b32 v143, v178 offset:40960
	s_or_b64 exec, exec, s[4:5]
	s_waitcnt lgkmcnt(0)
	v_add_u32_e32 v179, s33, v191
	v_add_f32_e32 v174, v174, v175
	v_mul_f32_e32 v147, v147, v178
	ds_read_b128 v[196:199], v179 offset:40960
	ds_read_b128 v[200:203], v179 offset:40992
	ds_read_b128 v[204:207], v179 offset:41024
	ds_read_b128 v[208:211], v179 offset:41056
	s_waitcnt lgkmcnt(0)
	s_nop 15
	v_pk_mul_f32 v[0:1], v[0:1], v[196:197]
	v_pk_mul_f32 v[2:3], v[2:3], v[198:199]
	v_pk_mul_f32 v[4:5], v[4:5], v[200:201]
	v_pk_mul_f32 v[6:7], v[6:7], v[202:203]
	v_pk_mul_f32 v[8:9], v[8:9], v[204:205]
	v_pk_mul_f32 v[10:11], v[10:11], v[206:207]
	v_pk_mul_f32 v[12:13], v[12:13], v[208:209]
	v_pk_mul_f32 v[14:15], v[14:15], v[210:211]
	v_pk_mul_f32 v[16:17], v[16:17], v[196:197]
	v_pk_mul_f32 v[18:19], v[18:19], v[198:199]
	v_pk_mul_f32 v[20:21], v[20:21], v[200:201]
	v_pk_mul_f32 v[22:23], v[22:23], v[202:203]
	v_pk_mul_f32 v[24:25], v[24:25], v[204:205]
	v_pk_mul_f32 v[26:27], v[26:27], v[206:207]
	v_pk_mul_f32 v[28:29], v[28:29], v[208:209]
	v_pk_mul_f32 v[30:31], v[30:31], v[210:211]
.Lat_nr_10:
	s_waitcnt vmcnt(2)
	s_barrier
	s_add_i32 m0, s22, 0x10000
	s_cmp_eq_u32 s23, 0
	global_load_lds_dwordx4 v128, s[12:13]
	s_cbranch_scc1 .Lat_k2_11
	s_add_i32 m0, s22, 0x12000
	s_nop 0
	global_load_lds_dwordx4 v129, s[12:13]
.Lat_k2_11:
	s_add_u32 s12, s12, 0x30000
	s_addc_u32 s13, s13, 0
	s_add_i32 m0, s22, 0x8000
	s_nop 0
	global_load_lds_dwordx4 v145, s[14:15]
	s_add_u32 s14, s14, 0x20000
	s_addc_u32 s15, s15, 0
	ds_read_b128 v[196:199], v194 offset:0
	ds_read_b128 v[200:203], v194 offset:512
	ds_read_b128 v[204:207], v194 offset:2048
	ds_read_b128 v[208:211], v194 offset:2560
	ds_read_b128 v[212:215], v194 offset:4096
	ds_read_b128 v[216:219], v194 offset:4608
	ds_read_b64_tr_b16 v[220:221], v127 offset:20480
	ds_read_b64_tr_b16 v[222:223], v127 offset:20992
	ds_read_b64_tr_b16 v[228:229], v127 offset:24576
	ds_read_b64_tr_b16 v[230:231], v127 offset:25088
	v_max_f32_e32 v149, v80, v81
	v_sub_f32_e32 v80, v80, v174
	v_sub_f32_e32 v81, v81, v174
	v_exp_f32_e32 v80, v80
	v_exp_f32_e32 v81, v81
	v_mov_b32_e32 v176, v80
	v_mov_b32_e32 v177, v81
	v_cvt_pk_bf16_f32 v80, v80, v81
	v_max3_f32 v149, v149, v82, v83
	v_sub_f32_e32 v82, v82, v174
	v_sub_f32_e32 v83, v83, v174
	v_exp_f32_e32 v82, v82
	s_waitcnt lgkmcnt(9)
	v_mfma_f32_32x32x16_bf16 v[48:63], v[196:199], v[110:113], 0
	ds_read_b128 v[196:199], v194 offset:6144
	ds_read_b64_tr_b16 v[224:225], v127 offset:21504
	ds_read_b64_tr_b16 v[226:227], v127 offset:22016
	v_exp_f32_e32 v83, v83
	v_add_f32_e32 v176, v82, v176
	v_add_f32_e32 v177, v83, v177
	v_cvt_pk_bf16_f32 v81, v82, v83
	v_max3_f32 v149, v149, v84, v85
	v_sub_f32_e32 v84, v84, v174
	v_sub_f32_e32 v85, v85, v174
	s_waitcnt lgkmcnt(11)
	v_mfma_f32_32x32x16_bf16 v[32:47], v[200:203], v[110:113], 0
	ds_read_b128 v[200:203], v194 offset:6656
	ds_read_b64_tr_b16 v[232:233], v127 offset:25600
	ds_read_b64_tr_b16 v[234:235], v127 offset:26112
	v_exp_f32_e32 v84, v84
	v_exp_f32_e32 v85, v85
	v_add_f32_e32 v176, v84, v176
	v_add_f32_e32 v177, v85, v177
	v_cvt_pk_bf16_f32 v82, v84, v85
	v_max3_f32 v149, v149, v86, v87
	v_sub_f32_e32 v86, v86, v174
	s_waitcnt lgkmcnt(13)
	v_mfma_f32_32x32x16_bf16 v[48:63], v[204:207], v[106:109], v[48:63]
	ds_read_b128 v[204:207], v194 offset:8192
	v_sub_f32_e32 v87, v87, v174
	v_exp_f32_e32 v86, v86
	v_exp_f32_e32 v87, v87
	v_add_f32_e32 v176, v86, v176
	v_add_f32_e32 v177, v87, v177
	v_cvt_pk_bf16_f32 v83, v86, v87
	v_max3_f32 v149, v149, v88, v89
	s_waitcnt lgkmcnt(13)
	v_mfma_f32_32x32x16_bf16 v[32:47], v[208:211], v[106:109], v[32:47]
	ds_read_b128 v[208:211], v194 offset:8704
	v_sub_f32_e32 v88, v88, v174
	v_sub_f32_e32 v89, v89, v174
	v_exp_f32_e32 v88, v88
	v_exp_f32_e32 v89, v89
	v_add_f32_e32 v176, v88, v176
	v_add_f32_e32 v177, v89, v177
	v_cvt_pk_bf16_f32 v84, v88, v89
	s_waitcnt lgkmcnt(13)
	v_mfma_f32_32x32x16_bf16 v[48:63], v[212:215], v[114:117], v[48:63]
	ds_read_b128 v[212:215], v194 offset:10240
	v_max3_f32 v149, v149, v90, v91
	v_sub_f32_e32 v90, v90, v174
	v_sub_f32_e32 v91, v91, v174
	v_exp_f32_e32 v90, v90
	v_exp_f32_e32 v91, v91
	v_add_f32_e32 v176, v90, v176
	v_add_f32_e32 v177, v91, v177
	s_waitcnt lgkmcnt(11)
	v_mfma_f32_32x32x16_bf16 v[0:15], v[80:83], v[220:223], v[0:15]
	ds_read_b64_tr_b16 v[236:237], v127 offset:22528
	ds_read_b64_tr_b16 v[238:239], v127 offset:23040
	v_cvt_pk_bf16_f32 v85, v90, v91
	v_max3_f32 v149, v149, v92, v93
	v_sub_f32_e32 v92, v92, v174
	v_sub_f32_e32 v93, v93, v174
	v_exp_f32_e32 v92, v92
	v_exp_f32_e32 v93, v93
	v_add_f32_e32 v176, v92, v176
	s_waitcnt lgkmcnt(11)
	v_mfma_f32_32x32x16_bf16 v[16:31], v[80:83], v[228:231], v[16:31]
	ds_read_b64_tr_b16 v[244:245], v127 offset:26624
	ds_read_b64_tr_b16 v[246:247], v127 offset:27136
	v_add_f32_e32 v177, v93, v177
	v_cvt_pk_bf16_f32 v86, v92, v93
	v_max3_f32 v149, v149, v94, v95
	v_sub_f32_e32 v94, v94, v174
	v_sub_f32_e32 v95, v95, v174
	v_exp_f32_e32 v94, v94
	v_exp_f32_e32 v95, v95
	v_mfma_f32_32x32x16_bf16 v[32:47], v[216:219], v[114:117], v[32:47]
	ds_read_b128 v[216:219], v194 offset:10752
	v_add_f32_e32 v176, v94, v176
	v_add_f32_e32 v177, v95, v177
	v_cvt_pk_bf16_f32 v87, v94, v95
	v_max3_f32 v149, v149, v64, v65
	v_sub_f32_e32 v64, v64, v174
	v_sub_f32_e32 v65, v65, v174
	v_exp_f32_e32 v64, v64
	s_waitcnt lgkmcnt(13)
	v_mfma_f32_32x32x16_bf16 v[48:63], v[196:199], v[118:121], v[48:63]
	v_exp_f32_e32 v65, v65
	v_add_f32_e32 v176, v64, v176
	v_add_f32_e32 v177, v65, v177
	v_cvt_pk_bf16_f32 v64, v64, v65
	v_max3_f32 v149, v149, v66, v67
	v_sub_f32_e32 v66, v66, v174
	v_sub_f32_e32 v67, v67, v174
	s_waitcnt lgkmcnt(10)
	v_mfma_f32_32x32x16_bf16 v[32:47], v[200:203], v[118:121], v[32:47]
	v_exp_f32_e32 v66, v66
	v_exp_f32_e32 v67, v67
	v_add_f32_e32 v176, v66, v176
	v_add_f32_e32 v177, v67, v177
	v_cvt_pk_bf16_f32 v65, v66, v67
	v_max3_f32 v149, v149, v68, v69
	v_sub_f32_e32 v68, v68, v174
	v_mfma_f32_32x32x16_bf16 v[0:15], v[84:87], v[224:227], v[0:15]
	ds_read_b64_tr_b16 v[240:241], v127 offset:23552
	ds_read_b64_tr_b16 v[242:243], v127 offset:24064
	v_sub_f32_e32 v69, v69, v174
	v_exp_f32_e32 v68, v68
	v_exp_f32_e32 v69, v69
	v_add_f32_e32 v176, v68, v176
	v_add_f32_e32 v177, v69, v177
	v_cvt_pk_bf16_f32 v66, v68, v69
	v_max3_f32 v149, v149, v70, v71
	s_waitcnt lgkmcnt(10)
	v_mfma_f32_32x32x16_bf16 v[16:31], v[84:87], v[232:235], v[16:31]
	ds_read_b64_tr_b16 v[122:123], v127 offset:27648
	ds_read_b64_tr_b16 v[124:125], v127 offset:28160
	v_sub_f32_e32 v70, v70, v174
	v_sub_f32_e32 v71, v71, v174
	v_exp_f32_e32 v70, v70
	v_exp_f32_e32 v71, v71
	v_add_f32_e32 v176, v70, v176
	v_add_f32_e32 v177, v71, v177
	v_cvt_pk_bf16_f32 v67, v70, v71
	s_waitcnt lgkmcnt(11)
; DEV float max3f(float a, float b, float c) { return fmaxf(fmaxf(a, b), c); }
; #define LOADK(t) do { const long kb_ = KBASE(t); kreg0 = *(const u32x4*)(K + (kb_ + lane) * 1536 + h * 96 + wid * 8); \
;         if (k2) kreg1 = *(const u32x4*)(K + (kb_ + lane) * 1536 + h * 96 + (8 + wid) * 8); } while (0)
; #define LOADV(t) do { const long kb_ = KBASE(t); vreg = *(const u32x4*)(V + (kb_ + 16 * (wid & 3) + (lane >> 2)) * 1024 + h * 64 + (wid >> 2) * 32 + (lane & 3) * 8); } while (0)
; #define STOREK(s) do { LAS unsigned char* st_ = sh + (s) * STG; *(LAS u32x4*)(st_ + wid * 1024 + lane * 16) = kreg0; if (k2) *(LAS u32x4*)(st_ + (8 + wid) * 1024 + lane * 16) = kreg1; } while (0)
; #define STOREV(s) do { LAS unsigned char* st_ = sh + (s) * STG; *(LAS u32x4*)(st_ + KST + wid * 1024 + lane * 16) = vreg; } while (0)
; DEV void attn_unit(int b, int h, int qb, const bf16_t* Q, const bf16_t* K, const bf16_t* V, bf16_t* O, LAS unsigned char* sh, const int tid, const float* qgain) {
;     ...
;     LOADK(0); LOADV(0); STOREK(0); STOREV(0); LOADK(1); STOREK(1); __syncthreads();
;     f32x16 pA0, pA1, pB0 = f32x16{}, pB1 = f32x16{};
;     QKT(pA0, pA1, 0);
;     { float m0 = pA0[0];
; #pragma unroll
;         for (int r = 0; r < 16; ++r) m0 = max3f(m0, pA0[r], pA1[r]);
;         mrun = fmaxf(m0, __shfl_xor(m0, 32)); }
;     for (int t = 0; t < NT - 2; t += 2) {
;         STEP(pA0, pA1, pB0, pB1, t, true);
;         STEP(pB0, pB1, pA0, pA1, t + 1, true);
;     }
;     STEP(pA0, pA1, pB0, pB1, NT - 2, true);
;     STEP(pB0, pB1, pA0, pA1, NT - 1, false);
	v_mfma_f32_32x32x16_bf16 v[48:63], v[204:207], v[102:105], v[48:63]
	v_max3_f32 v149, v149, v72, v73
	v_sub_f32_e32 v72, v72, v174
	v_sub_f32_e32 v73, v73, v174
	v_exp_f32_e32 v72, v72
	v_exp_f32_e32 v73, v73
	v_add_f32_e32 v176, v72, v176
	v_add_f32_e32 v177, v73, v177
	s_waitcnt lgkmcnt(10)
	v_mfma_f32_32x32x16_bf16 v[32:47], v[208:211], v[102:105], v[32:47]
	v_cvt_pk_bf16_f32 v68, v72, v73
	v_max3_f32 v149, v149, v74, v75
	v_sub_f32_e32 v74, v74, v174
	v_sub_f32_e32 v75, v75, v174
	v_exp_f32_e32 v74, v74
	v_exp_f32_e32 v75, v75
	v_add_f32_e32 v176, v74, v176
	s_waitcnt lgkmcnt(7)
	v_mfma_f32_32x32x16_bf16 v[0:15], v[64:67], v[236:239], v[0:15]
	v_add_f32_e32 v177, v75, v177
	v_cvt_pk_bf16_f32 v69, v74, v75
	v_max3_f32 v149, v149, v76, v77
	v_sub_f32_e32 v76, v76, v174
	v_sub_f32_e32 v77, v77, v174
	v_exp_f32_e32 v76, v76
	v_exp_f32_e32 v77, v77
	s_waitcnt lgkmcnt(5)
	v_mfma_f32_32x32x16_bf16 v[16:31], v[64:67], v[244:247], v[16:31]
	v_add_f32_e32 v176, v76, v176
	v_add_f32_e32 v177, v77, v177
	v_cvt_pk_bf16_f32 v70, v76, v77
	v_max3_f32 v149, v149, v78, v79
	v_sub_f32_e32 v78, v78, v174
	v_sub_f32_e32 v79, v79, v174
	v_exp_f32_e32 v78, v78
	v_mfma_f32_32x32x16_bf16 v[48:63], v[212:215], v[98:101], v[48:63]
	v_exp_f32_e32 v79, v79
	v_add_f32_e32 v176, v78, v176
	v_add_f32_e32 v177, v79, v177
	v_cvt_pk_bf16_f32 v71, v78, v79
	v_add_f32_e32 v179, v176, v177
	v_mov_b32_e32 v175, v149
	v_mov_b32_e32 v178, v149
	s_waitcnt lgkmcnt(4)
	v_mfma_f32_32x32x16_bf16 v[32:47], v[216:219], v[98:101], v[32:47]
	v_add_f32_e32 v147, v147, v179
	s_nop 1
	v_permlane32_swap_b32_e32 v175, v178
	v_max_f32_e32 v175, v175, v178
	v_sub_f32_e32 v175, v175, v174
	v_cmp_lt_f32_e32 vcc, s43, v175
	s_waitcnt lgkmcnt(2)
	v_mfma_f32_32x32x16_bf16 v[0:15], v[68:71], v[240:243], v[0:15]
	s_waitcnt lgkmcnt(0)
	v_mfma_f32_32x32x16_bf16 v[16:31], v[68:71], v[122:125], v[16:31]
	s_cbranch_vccz .Lat_nr_12
	v_max_f32_e32 v175, v175, v175
	v_max_f32_e32 v175, 0, v175
	v_exp_f32_e64 v178, -v175
	s_and_saveexec_b64 s[4:5], s[2:3]
	ds_write_b32 v143, v178 offset:40960
	s_or_b64 exec, exec, s[4:5]
	s_waitcnt lgkmcnt(0)
	v_add_u32_e32 v179, s33, v191
	v_add_f32_e32 v174, v174, v175
	v_mul_f32_e32 v147, v147, v178
	ds_read_b128 v[196:199], v179 offset:40960
	ds_read_b128 v[200:203], v179 offset:40992
	ds_read_b128 v[204:207], v179 offset:41024
	ds_read_b128 v[208:211], v179 offset:41056
	s_waitcnt lgkmcnt(0)
	s_nop 15
	v_pk_mul_f32 v[0:1], v[0:1], v[196:197]
	v_pk_mul_f32 v[2:3], v[2:3], v[198:199]
	v_pk_mul_f32 v[4:5], v[4:5], v[200:201]
	v_pk_mul_f32 v[6:7], v[6:7], v[202:203]
	v_pk_mul_f32 v[8:9], v[8:9], v[204:205]
	v_pk_mul_f32 v[10:11], v[10:11], v[206:207]
	v_pk_mul_f32 v[12:13], v[12:13], v[208:209]
	v_pk_mul_f32 v[14:15], v[14:15], v[210:211]
	v_pk_mul_f32 v[16:17], v[16:17], v[196:197]
	v_pk_mul_f32 v[18:19], v[18:19], v[198:199]
	v_pk_mul_f32 v[20:21], v[20:21], v[200:201]
	v_pk_mul_f32 v[22:23], v[22:23], v[202:203]
	v_pk_mul_f32 v[24:25], v[24:25], v[204:205]
	v_pk_mul_f32 v[26:27], v[26:27], v[206:207]
	v_pk_mul_f32 v[28:29], v[28:29], v[208:209]
	v_pk_mul_f32 v[30:31], v[30:31], v[210:211]
.Lat_nr_12:
	s_waitcnt vmcnt(2)
	s_barrier
	s_sub_u32 s24, s24, 1
	s_cmp_lg_u32 s24, 0
	s_cbranch_scc1 .Lat_loop_4
	s_add_i32 m0, s22, 0x15000
	s_cmp_eq_u32 s23, 0
	global_load_lds_dwordx4 v128, s[12:13]
	s_cbranch_scc1 .Lat_k2_13
	s_add_i32 m0, s22, 0x17000
	s_nop 0
	global_load_lds_dwordx4 v129, s[12:13]
.Lat_k2_13:
	s_add_i32 m0, s22, 0x13000
	s_nop 0
	global_load_lds_dwordx4 v145, s[14:15]
	s_add_u32 s14, s14, 0x20000
	s_addc_u32 s15, s15, 0
	ds_read_b128 v[196:199], v194 offset:20480
	ds_read_b128 v[200:203], v194 offset:20992
	ds_read_b128 v[204:207], v194 offset:22528
	ds_read_b128 v[208:211], v194 offset:23040
	ds_read_b128 v[212:215], v194 offset:24576
	ds_read_b128 v[216:219], v194 offset:25088
	ds_read_b64_tr_b16 v[220:221], v139 offset:0
	ds_read_b64_tr_b16 v[222:223], v139 offset:512
	ds_read_b64_tr_b16 v[228:229], v139 offset:4096
	ds_read_b64_tr_b16 v[230:231], v139 offset:4608
	v_max_f32_e32 v149, v48, v49
	v_sub_f32_e32 v48, v48, v174
	v_sub_f32_e32 v49, v49, v174
	v_exp_f32_e32 v48, v48
	v_exp_f32_e32 v49, v49
	v_mov_b32_e32 v176, v48
	v_mov_b32_e32 v177, v49
	v_cvt_pk_bf16_f32 v48, v48, v49
	v_max3_f32 v149, v149, v50, v51
	v_sub_f32_e32 v50, v50, v174
	v_sub_f32_e32 v51, v51, v174
	v_exp_f32_e32 v50, v50
	s_waitcnt lgkmcnt(9)
	v_mfma_f32_32x32x16_bf16 v[80:95], v[196:199], v[110:113], 0
	ds_read_b128 v[196:199], v194 offset:26624
	ds_read_b64_tr_b16 v[224:225], v139 offset:1024
	ds_read_b64_tr_b16 v[226:227], v139 offset:1536
	v_exp_f32_e32 v51, v51
	v_add_f32_e32 v176, v50, v176
	v_add_f32_e32 v177, v51, v177
	v_cvt_pk_bf16_f32 v49, v50, v51
	v_max3_f32 v149, v149, v52, v53
	v_sub_f32_e32 v52, v52, v174
	v_sub_f32_e32 v53, v53, v174
	s_waitcnt lgkmcnt(11)
	v_mfma_f32_32x32x16_bf16 v[64:79], v[200:203], v[110:113], 0
	ds_read_b128 v[200:203], v194 offset:27136
	ds_read_b64_tr_b16 v[232:233], v139 offset:5120
	ds_read_b64_tr_b16 v[234:235], v139 offset:5632
	v_exp_f32_e32 v52, v52
	v_exp_f32_e32 v53, v53
	v_add_f32_e32 v176, v52, v176
	v_add_f32_e32 v177, v53, v177
	v_cvt_pk_bf16_f32 v50, v52, v53
	v_max3_f32 v149, v149, v54, v55
	v_sub_f32_e32 v54, v54, v174
	s_waitcnt lgkmcnt(13)
	v_mfma_f32_32x32x16_bf16 v[80:95], v[204:207], v[106:109], v[80:95]
	ds_read_b128 v[204:207], v194 offset:28672
	v_sub_f32_e32 v55, v55, v174
	v_exp_f32_e32 v54, v54
	v_exp_f32_e32 v55, v55
	v_add_f32_e32 v176, v54, v176
	v_add_f32_e32 v177, v55, v177
	v_cvt_pk_bf16_f32 v51, v54, v55
	v_max3_f32 v149, v149, v56, v57
	s_waitcnt lgkmcnt(13)
	v_mfma_f32_32x32x16_bf16 v[64:79], v[208:211], v[106:109], v[64:79]
	ds_read_b128 v[208:211], v194 offset:29184
	v_sub_f32_e32 v56, v56, v174
	v_sub_f32_e32 v57, v57, v174
	v_exp_f32_e32 v56, v56
	v_exp_f32_e32 v57, v57
	v_add_f32_e32 v176, v56, v176
	v_add_f32_e32 v177, v57, v177
	v_cvt_pk_bf16_f32 v52, v56, v57
	s_waitcnt lgkmcnt(13)
	v_mfma_f32_32x32x16_bf16 v[80:95], v[212:215], v[114:117], v[80:95]
	ds_read_b128 v[212:215], v194 offset:30720
	v_max3_f32 v149, v149, v58, v59
	v_sub_f32_e32 v58, v58, v174
	v_sub_f32_e32 v59, v59, v174
	v_exp_f32_e32 v58, v58
	v_exp_f32_e32 v59, v59
	v_add_f32_e32 v176, v58, v176
	v_add_f32_e32 v177, v59, v177
	s_waitcnt lgkmcnt(11)
	v_mfma_f32_32x32x16_bf16 v[0:15], v[48:51], v[220:223], v[0:15]
	ds_read_b64_tr_b16 v[236:237], v139 offset:2048
	ds_read_b64_tr_b16 v[238:239], v139 offset:2560
	v_cvt_pk_bf16_f32 v53, v58, v59
	v_max3_f32 v149, v149, v60, v61
	v_sub_f32_e32 v60, v60, v174
	v_sub_f32_e32 v61, v61, v174
	v_exp_f32_e32 v60, v60
	v_exp_f32_e32 v61, v61
	v_add_f32_e32 v176, v60, v176
	s_waitcnt lgkmcnt(11)
	v_mfma_f32_32x32x16_bf16 v[16:31], v[48:51], v[228:231], v[16:31]
	ds_read_b64_tr_b16 v[244:245], v139 offset:6144
	ds_read_b64_tr_b16 v[246:247], v139 offset:6656
	v_add_f32_e32 v177, v61, v177
	v_cvt_pk_bf16_f32 v54, v60, v61
	v_max3_f32 v149, v149, v62, v63
	v_sub_f32_e32 v62, v62, v174
	v_sub_f32_e32 v63, v63, v174
	v_exp_f32_e32 v62, v62
	v_exp_f32_e32 v63, v63
	v_mfma_f32_32x32x16_bf16 v[64:79], v[216:219], v[114:117], v[64:79]
	ds_read_b128 v[216:219], v194 offset:31232
	v_add_f32_e32 v176, v62, v176
	v_add_f32_e32 v177, v63, v177
	v_cvt_pk_bf16_f32 v55, v62, v63
	v_max3_f32 v149, v149, v32, v33
	v_sub_f32_e32 v32, v32, v174
	v_sub_f32_e32 v33, v33, v174
	v_exp_f32_e32 v32, v32
	s_waitcnt lgkmcnt(13)
	v_mfma_f32_32x32x16_bf16 v[80:95], v[196:199], v[118:121], v[80:95]
	v_exp_f32_e32 v33, v33
	v_add_f32_e32 v176, v32, v176
	v_add_f32_e32 v177, v33, v177
	v_cvt_pk_bf16_f32 v32, v32, v33
	v_max3_f32 v149, v149, v34, v35
	v_sub_f32_e32 v34, v34, v174
	v_sub_f32_e32 v35, v35, v174
	s_waitcnt lgkmcnt(10)
	v_mfma_f32_32x32x16_bf16 v[64:79], v[200:203], v[118:121], v[64:79]
	v_exp_f32_e32 v34, v34
	v_exp_f32_e32 v35, v35
	v_add_f32_e32 v176, v34, v176
	v_add_f32_e32 v177, v35, v177
	v_cvt_pk_bf16_f32 v33, v34, v35
	v_max3_f32 v149, v149, v36, v37
	v_sub_f32_e32 v36, v36, v174
	v_mfma_f32_32x32x16_bf16 v[0:15], v[52:55], v[224:227], v[0:15]
	ds_read_b64_tr_b16 v[240:241], v139 offset:3072
	ds_read_b64_tr_b16 v[242:243], v139 offset:3584
	v_sub_f32_e32 v37, v37, v174
	v_exp_f32_e32 v36, v36
	v_exp_f32_e32 v37, v37
	v_add_f32_e32 v176, v36, v176
	v_add_f32_e32 v177, v37, v177
	v_cvt_pk_bf16_f32 v34, v36, v37
	v_max3_f32 v149, v149, v38, v39
	s_waitcnt lgkmcnt(10)
	v_mfma_f32_32x32x16_bf16 v[16:31], v[52:55], v[232:235], v[16:31]
	ds_read_b64_tr_b16 v[122:123], v139 offset:7168
	ds_read_b64_tr_b16 v[124:125], v139 offset:7680
	v_sub_f32_e32 v38, v38, v174
	v_sub_f32_e32 v39, v39, v174
	v_exp_f32_e32 v38, v38
	v_exp_f32_e32 v39, v39
	v_add_f32_e32 v176, v38, v176
	v_add_f32_e32 v177, v39, v177
	v_cvt_pk_bf16_f32 v35, v38, v39
	s_waitcnt lgkmcnt(11)
	v_mfma_f32_32x32x16_bf16 v[80:95], v[204:207], v[102:105], v[80:95]
	v_max3_f32 v149, v149, v40, v41
	v_sub_f32_e32 v40, v40, v174
	v_sub_f32_e32 v41, v41, v174
	v_exp_f32_e32 v40, v40
	v_exp_f32_e32 v41, v41
	v_add_f32_e32 v176, v40, v176
	v_add_f32_e32 v177, v41, v177
	s_waitcnt lgkmcnt(10)
	v_mfma_f32_32x32x16_bf16 v[64:79], v[208:211], v[102:105], v[64:79]
	v_cvt_pk_bf16_f32 v36, v40, v41
	v_max3_f32 v149, v149, v42, v43
	v_sub_f32_e32 v42, v42, v174
	v_sub_f32_e32 v43, v43, v174
	v_exp_f32_e32 v42, v42
	v_exp_f32_e32 v43, v43
	v_add_f32_e32 v176, v42, v176
	s_waitcnt lgkmcnt(7)
	v_mfma_f32_32x32x16_bf16 v[0:15], v[32:35], v[236:239], v[0:15]
	v_add_f32_e32 v177, v43, v177
	v_cvt_pk_bf16_f32 v37, v42, v43
	v_max3_f32 v149, v149, v44, v45
	v_sub_f32_e32 v44, v44, v174
	v_sub_f32_e32 v45, v45, v174
	v_exp_f32_e32 v44, v44
	v_exp_f32_e32 v45, v45
	s_waitcnt lgkmcnt(5)
	v_mfma_f32_32x32x16_bf16 v[16:31], v[32:35], v[244:247], v[16:31]
	v_add_f32_e32 v176, v44, v176
	v_add_f32_e32 v177, v45, v177
	v_cvt_pk_bf16_f32 v38, v44, v45
	v_max3_f32 v149, v149, v46, v47
	v_sub_f32_e32 v46, v46, v174
	v_sub_f32_e32 v47, v47, v174
	v_exp_f32_e32 v46, v46
	v_mfma_f32_32x32x16_bf16 v[80:95], v[212:215], v[98:101], v[80:95]
	v_exp_f32_e32 v47, v47
	v_add_f32_e32 v176, v46, v176
	v_add_f32_e32 v177, v47, v177
	v_cvt_pk_bf16_f32 v39, v46, v47
	v_add_f32_e32 v179, v176, v177
	v_mov_b32_e32 v175, v149
	v_mov_b32_e32 v178, v149
	s_waitcnt lgkmcnt(4)
	v_mfma_f32_32x32x16_bf16 v[64:79], v[216:219], v[98:101], v[64:79]
	v_add_f32_e32 v147, v147, v179
	s_nop 1
	v_permlane32_swap_b32_e32 v175, v178
	v_max_f32_e32 v175, v175, v178
	v_sub_f32_e32 v175, v175, v174
	v_cmp_lt_f32_e32 vcc, s43, v175
	s_waitcnt lgkmcnt(2)
	v_mfma_f32_32x32x16_bf16 v[0:15], v[36:39], v[240:243], v[0:15]
	s_waitcnt lgkmcnt(0)
	v_mfma_f32_32x32x16_bf16 v[16:31], v[36:39], v[122:125], v[16:31]
	s_cbranch_vccz .Lat_nr_14
	v_max_f32_e32 v175, v175, v175
	v_max_f32_e32 v175, 0, v175
	v_exp_f32_e64 v178, -v175
	s_and_saveexec_b64 s[4:5], s[2:3]
	ds_write_b32 v143, v178 offset:40960
	s_or_b64 exec, exec, s[4:5]
	s_waitcnt lgkmcnt(0)
	v_add_u32_e32 v179, s33, v191
	v_add_f32_e32 v174, v174, v175
	v_mul_f32_e32 v147, v147, v178
	ds_read_b128 v[196:199], v179 offset:40960
	ds_read_b128 v[200:203], v179 offset:40992
	ds_read_b128 v[204:207], v179 offset:41024
	ds_read_b128 v[208:211], v179 offset:41056
	s_waitcnt lgkmcnt(0)
	s_nop 15
	v_pk_mul_f32 v[0:1], v[0:1], v[196:197]
	v_pk_mul_f32 v[2:3], v[2:3], v[198:199]
	v_pk_mul_f32 v[4:5], v[4:5], v[200:201]
	v_pk_mul_f32 v[6:7], v[6:7], v[202:203]
	v_pk_mul_f32 v[8:9], v[8:9], v[204:205]
	v_pk_mul_f32 v[10:11], v[10:11], v[206:207]
	v_pk_mul_f32 v[12:13], v[12:13], v[208:209]
	v_pk_mul_f32 v[14:15], v[14:15], v[210:211]
	v_pk_mul_f32 v[16:17], v[16:17], v[196:197]
	v_pk_mul_f32 v[18:19], v[18:19], v[198:199]
	v_pk_mul_f32 v[20:21], v[20:21], v[200:201]
	v_pk_mul_f32 v[22:23], v[22:23], v[202:203]
	v_pk_mul_f32 v[24:25], v[24:25], v[204:205]
	v_pk_mul_f32 v[26:27], v[26:27], v[206:207]
	v_pk_mul_f32 v[28:29], v[28:29], v[208:209]
	v_pk_mul_f32 v[30:31], v[30:31], v[210:211]
; DEV float max3f(float a, float b, float c) { return fmaxf(fmaxf(a, b), c); }
; #define LOADK(t) do { const long kb_ = KBASE(t); kreg0 = *(const u32x4*)(K + (kb_ + lane) * 1536 + h * 96 + wid * 8); \
;         if (k2) kreg1 = *(const u32x4*)(K + (kb_ + lane) * 1536 + h * 96 + (8 + wid) * 8); } while (0)
; #define LOADV(t) do { const long kb_ = KBASE(t); vreg = *(const u32x4*)(V + (kb_ + 16 * (wid & 3) + (lane >> 2)) * 1024 + h * 64 + (wid >> 2) * 32 + (lane & 3) * 8); } while (0)
; #define STOREK(s) do { LAS unsigned char* st_ = sh + (s) * STG; *(LAS u32x4*)(st_ + wid * 1024 + lane * 16) = kreg0; if (k2) *(LAS u32x4*)(st_ + (8 + wid) * 1024 + lane * 16) = kreg1; } while (0)
; #define STOREV(s) do { LAS unsigned char* st_ = sh + (s) * STG; *(LAS u32x4*)(st_ + KST + wid * 1024 + lane * 16) = vreg; } while (0)
; DEV void attn_unit(int b, int h, int qb, const bf16_t* Q, const bf16_t* K, const bf16_t* V, bf16_t* O, LAS unsigned char* sh, const int tid, const float* qgain) {
;     ...
;     LOADK(0); LOADV(0); STOREK(0); STOREV(0); LOADK(1); STOREK(1); __syncthreads();
;     f32x16 pA0, pA1, pB0 = f32x16{}, pB1 = f32x16{};
;     QKT(pA0, pA1, 0);
;     { float m0 = pA0[0];
; #pragma unroll
;         for (int r = 0; r < 16; ++r) m0 = max3f(m0, pA0[r], pA1[r]);
;         mrun = fmaxf(m0, __shfl_xor(m0, 32)); }
;     for (int t = 0; t < NT - 2; t += 2) {
;         STEP(pA0, pA1, pB0, pB1, t, true);
;         STEP(pB0, pB1, pA0, pA1, t + 1, true);
;     }
;     STEP(pA0, pA1, pB0, pB1, NT - 2, true);
;     STEP(pB0, pB1, pA0, pA1, NT - 1, false);
.Lat_nr_14:
	s_waitcnt vmcnt(2)
	s_barrier
	s_mov_b64 s[12:13], s[36:37]
	s_add_i32 m0, s22, 0x0
	s_cmp_eq_u32 s23, 0
	global_load_lds_dwordx4 v128, s[12:13]
	s_cbranch_scc1 .Lat_k2_15
	s_add_i32 m0, s22, 0x2000
	s_nop 0
	global_load_lds_dwordx4 v129, s[12:13]
.Lat_k2_15:
	s_add_u32 s12, s12, 0x30000
	s_addc_u32 s13, s13, 0
	s_add_i32 m0, s22, 0x18000
	s_nop 0
	global_load_lds_dwordx4 v145, s[14:15]
	ds_read_b128 v[196:199], v126 offset:0
	ds_read_b128 v[200:203], v126 offset:512
	ds_read_b128 v[204:207], v126 offset:2048
	ds_read_b128 v[208:211], v126 offset:2560
	ds_read_b128 v[212:215], v126 offset:4096
	ds_read_b128 v[216:219], v126 offset:4608
	ds_read_b64_tr_b16 v[220:221], v139 offset:20480
	ds_read_b64_tr_b16 v[222:223], v139 offset:20992
	ds_read_b64_tr_b16 v[228:229], v139 offset:24576
	ds_read_b64_tr_b16 v[230:231], v139 offset:25088
	v_max_f32_e32 v149, v80, v81
	v_sub_f32_e32 v80, v80, v174
	v_sub_f32_e32 v81, v81, v174
	v_exp_f32_e32 v80, v80
	v_exp_f32_e32 v81, v81
	v_mov_b32_e32 v176, v80
	v_mov_b32_e32 v177, v81
	v_cvt_pk_bf16_f32 v80, v80, v81
	v_max3_f32 v149, v149, v82, v83
	v_sub_f32_e32 v82, v82, v174
	v_sub_f32_e32 v83, v83, v174
	v_exp_f32_e32 v82, v82
	s_waitcnt lgkmcnt(9)
	v_mfma_f32_32x32x16_bf16 v[48:63], v[196:199], v[110:113], 0
	ds_read_b128 v[196:199], v126 offset:6144
	ds_read_b64_tr_b16 v[224:225], v139 offset:21504
	ds_read_b64_tr_b16 v[226:227], v139 offset:22016
	v_exp_f32_e32 v83, v83
	v_add_f32_e32 v176, v82, v176
	v_add_f32_e32 v177, v83, v177
	v_cvt_pk_bf16_f32 v81, v82, v83
	v_max3_f32 v149, v149, v84, v85
	v_sub_f32_e32 v84, v84, v174
	v_sub_f32_e32 v85, v85, v174
	s_waitcnt lgkmcnt(11)
	v_mfma_f32_32x32x16_bf16 v[32:47], v[200:203], v[110:113], 0
	ds_read_b128 v[200:203], v126 offset:6656
	ds_read_b64_tr_b16 v[232:233], v139 offset:25600
	ds_read_b64_tr_b16 v[234:235], v139 offset:26112
	v_exp_f32_e32 v84, v84
	v_exp_f32_e32 v85, v85
	v_add_f32_e32 v176, v84, v176
	v_add_f32_e32 v177, v85, v177
	v_cvt_pk_bf16_f32 v82, v84, v85
	v_max3_f32 v149, v149, v86, v87
	v_sub_f32_e32 v86, v86, v174
	s_waitcnt lgkmcnt(13)
	v_mfma_f32_32x32x16_bf16 v[48:63], v[204:207], v[106:109], v[48:63]
	ds_read_b128 v[204:207], v126 offset:8192
	v_sub_f32_e32 v87, v87, v174
	v_exp_f32_e32 v86, v86
	v_exp_f32_e32 v87, v87
	v_add_f32_e32 v176, v86, v176
	v_add_f32_e32 v177, v87, v177
	v_cvt_pk_bf16_f32 v83, v86, v87
	v_max3_f32 v149, v149, v88, v89
	s_waitcnt lgkmcnt(13)
	v_mfma_f32_32x32x16_bf16 v[32:47], v[208:211], v[106:109], v[32:47]
	ds_read_b128 v[208:211], v126 offset:8704
	v_sub_f32_e32 v88, v88, v174
	v_sub_f32_e32 v89, v89, v174
	v_exp_f32_e32 v88, v88
	v_exp_f32_e32 v89, v89
	v_add_f32_e32 v176, v88, v176
	v_add_f32_e32 v177, v89, v177
	v_cvt_pk_bf16_f32 v84, v88, v89
	s_waitcnt lgkmcnt(13)
	v_mfma_f32_32x32x16_bf16 v[48:63], v[212:215], v[114:117], v[48:63]
	ds_read_b128 v[212:215], v126 offset:10240
	v_max3_f32 v149, v149, v90, v91
	v_sub_f32_e32 v90, v90, v174
	v_sub_f32_e32 v91, v91, v174
	v_exp_f32_e32 v90, v90
	v_exp_f32_e32 v91, v91
	v_add_f32_e32 v176, v90, v176
	v_add_f32_e32 v177, v91, v177
	s_waitcnt lgkmcnt(11)
	v_mfma_f32_32x32x16_bf16 v[0:15], v[80:83], v[220:223], v[0:15]
	ds_read_b64_tr_b16 v[236:237], v139 offset:22528
	ds_read_b64_tr_b16 v[238:239], v139 offset:23040
	v_cvt_pk_bf16_f32 v85, v90, v91
	v_max3_f32 v149, v149, v92, v93
	v_sub_f32_e32 v92, v92, v174
	v_sub_f32_e32 v93, v93, v174
	v_exp_f32_e32 v92, v92
	v_exp_f32_e32 v93, v93
	v_add_f32_e32 v176, v92, v176
	s_waitcnt lgkmcnt(11)
	v_mfma_f32_32x32x16_bf16 v[16:31], v[80:83], v[228:231], v[16:31]
	ds_read_b64_tr_b16 v[244:245], v139 offset:26624
	ds_read_b64_tr_b16 v[246:247], v139 offset:27136
	v_add_f32_e32 v177, v93, v177
	v_cvt_pk_bf16_f32 v86, v92, v93
	v_max3_f32 v149, v149, v94, v95
	v_sub_f32_e32 v94, v94, v174
	v_sub_f32_e32 v95, v95, v174
	v_exp_f32_e32 v94, v94
	v_exp_f32_e32 v95, v95
	v_mfma_f32_32x32x16_bf16 v[32:47], v[216:219], v[114:117], v[32:47]
	ds_read_b128 v[216:219], v126 offset:10752
	v_add_f32_e32 v176, v94, v176
	v_add_f32_e32 v177, v95, v177
	v_cvt_pk_bf16_f32 v87, v94, v95
	v_max3_f32 v149, v149, v64, v65
	v_sub_f32_e32 v64, v64, v174
	v_sub_f32_e32 v65, v65, v174
	v_exp_f32_e32 v64, v64
	s_waitcnt lgkmcnt(13)
	v_mfma_f32_32x32x16_bf16 v[48:63], v[196:199], v[118:121], v[48:63]
	v_exp_f32_e32 v65, v65
	v_add_f32_e32 v176, v64, v176
	v_add_f32_e32 v177, v65, v177
	v_cvt_pk_bf16_f32 v64, v64, v65
	v_max3_f32 v149, v149, v66, v67
	v_sub_f32_e32 v66, v66, v174
	v_sub_f32_e32 v67, v67, v174
	s_waitcnt lgkmcnt(10)
	v_mfma_f32_32x32x16_bf16 v[32:47], v[200:203], v[118:121], v[32:47]
	v_exp_f32_e32 v66, v66
	v_exp_f32_e32 v67, v67
	v_add_f32_e32 v176, v66, v176
	v_add_f32_e32 v177, v67, v177
	v_cvt_pk_bf16_f32 v65, v66, v67
	v_max3_f32 v149, v149, v68, v69
	v_sub_f32_e32 v68, v68, v174
	v_mfma_f32_32x32x16_bf16 v[0:15], v[84:87], v[224:227], v[0:15]
	ds_read_b64_tr_b16 v[240:241], v139 offset:23552
	ds_read_b64_tr_b16 v[242:243], v139 offset:24064
	v_sub_f32_e32 v69, v69, v174
	v_exp_f32_e32 v68, v68
	v_exp_f32_e32 v69, v69
	v_add_f32_e32 v176, v68, v176
	v_add_f32_e32 v177, v69, v177
	v_cvt_pk_bf16_f32 v66, v68, v69
	v_max3_f32 v149, v149, v70, v71
	s_waitcnt lgkmcnt(10)
	v_mfma_f32_32x32x16_bf16 v[16:31], v[84:87], v[232:235], v[16:31]
	ds_read_b64_tr_b16 v[122:123], v139 offset:27648
	ds_read_b64_tr_b16 v[124:125], v139 offset:28160
	v_sub_f32_e32 v70, v70, v174
	v_sub_f32_e32 v71, v71, v174
	v_exp_f32_e32 v70, v70
	v_exp_f32_e32 v71, v71
	v_add_f32_e32 v176, v70, v176
	v_add_f32_e32 v177, v71, v177
	v_cvt_pk_bf16_f32 v67, v70, v71
	s_waitcnt lgkmcnt(11)
	v_mfma_f32_32x32x16_bf16 v[48:63], v[204:207], v[102:105], v[48:63]
	v_max3_f32 v149, v149, v72, v73
	v_sub_f32_e32 v72, v72, v174
	v_sub_f32_e32 v73, v73, v174
	v_exp_f32_e32 v72, v72
	v_exp_f32_e32 v73, v73
	v_add_f32_e32 v176, v72, v176
	v_add_f32_e32 v177, v73, v177
	s_waitcnt lgkmcnt(10)
	v_mfma_f32_32x32x16_bf16 v[32:47], v[208:211], v[102:105], v[32:47]
	v_cvt_pk_bf16_f32 v68, v72, v73
	v_max3_f32 v149, v149, v74, v75
	v_sub_f32_e32 v74, v74, v174
	v_sub_f32_e32 v75, v75, v174
	v_exp_f32_e32 v74, v74
	v_exp_f32_e32 v75, v75
	v_add_f32_e32 v176, v74, v176
	s_waitcnt lgkmcnt(7)
	v_mfma_f32_32x32x16_bf16 v[0:15], v[64:67], v[236:239], v[0:15]
	v_add_f32_e32 v177, v75, v177
	v_cvt_pk_bf16_f32 v69, v74, v75
	v_max3_f32 v149, v149, v76, v77
	v_sub_f32_e32 v76, v76, v174
	v_sub_f32_e32 v77, v77, v174
	v_exp_f32_e32 v76, v76
	v_exp_f32_e32 v77, v77
	s_waitcnt lgkmcnt(5)
	v_mfma_f32_32x32x16_bf16 v[16:31], v[64:67], v[244:247], v[16:31]
	v_add_f32_e32 v176, v76, v176
	v_add_f32_e32 v177, v77, v177
	v_cvt_pk_bf16_f32 v70, v76, v77
	v_max3_f32 v149, v149, v78, v79
	v_sub_f32_e32 v78, v78, v174
	v_sub_f32_e32 v79, v79, v174
	v_exp_f32_e32 v78, v78
	v_mfma_f32_32x32x16_bf16 v[48:63], v[212:215], v[98:101], v[48:63]
	v_exp_f32_e32 v79, v79
	v_add_f32_e32 v176, v78, v176
	v_add_f32_e32 v177, v79, v177
	v_cvt_pk_bf16_f32 v71, v78, v79
	v_add_f32_e32 v179, v176, v177
	v_mov_b32_e32 v175, v149
	v_mov_b32_e32 v178, v149
	s_waitcnt lgkmcnt(4)
	v_mfma_f32_32x32x16_bf16 v[32:47], v[216:219], v[98:101], v[32:47]
	v_add_f32_e32 v147, v147, v179
	s_nop 1
	v_permlane32_swap_b32_e32 v175, v178
	v_max_f32_e32 v175, v175, v178
	v_sub_f32_e32 v175, v175, v174
	v_cmp_lt_f32_e32 vcc, s43, v175
	s_waitcnt lgkmcnt(2)
	v_mfma_f32_32x32x16_bf16 v[0:15], v[68:71], v[240:243], v[0:15]
	s_waitcnt lgkmcnt(0)
	v_mfma_f32_32x32x16_bf16 v[16:31], v[68:71], v[122:125], v[16:31]
	s_cbranch_vccz .Lat_nr_16
	v_max_f32_e32 v175, v175, v175
	v_max_f32_e32 v175, 0, v175
	v_exp_f32_e64 v178, -v175
	s_and_saveexec_b64 s[4:5], s[2:3]
	ds_write_b32 v143, v178 offset:40960
	s_or_b64 exec, exec, s[4:5]
	s_waitcnt lgkmcnt(0)
	v_add_u32_e32 v179, s33, v191
	v_add_f32_e32 v174, v174, v175
	v_mul_f32_e32 v147, v147, v178
	ds_read_b128 v[196:199], v179 offset:40960
	ds_read_b128 v[200:203], v179 offset:40992
	ds_read_b128 v[204:207], v179 offset:41024
	ds_read_b128 v[208:211], v179 offset:41056
	s_waitcnt lgkmcnt(0)
	s_nop 15
	v_pk_mul_f32 v[0:1], v[0:1], v[196:197]
	v_pk_mul_f32 v[2:3], v[2:3], v[198:199]
	v_pk_mul_f32 v[4:5], v[4:5], v[200:201]
	v_pk_mul_f32 v[6:7], v[6:7], v[202:203]
	v_pk_mul_f32 v[8:9], v[8:9], v[204:205]
	v_pk_mul_f32 v[10:11], v[10:11], v[206:207]
	v_pk_mul_f32 v[12:13], v[12:13], v[208:209]
	v_pk_mul_f32 v[14:15], v[14:15], v[210:211]
	v_pk_mul_f32 v[16:17], v[16:17], v[196:197]
	v_pk_mul_f32 v[18:19], v[18:19], v[198:199]
	v_pk_mul_f32 v[20:21], v[20:21], v[200:201]
	v_pk_mul_f32 v[22:23], v[22:23], v[202:203]
	v_pk_mul_f32 v[24:25], v[24:25], v[204:205]
	v_pk_mul_f32 v[26:27], v[26:27], v[206:207]
	v_pk_mul_f32 v[28:29], v[28:29], v[208:209]
	v_pk_mul_f32 v[30:31], v[30:31], v[210:211]

; DEV float max3f(float a, float b, float c) { return fmaxf(fmaxf(a, b), c); }
; #define LOADK(t) do { const long kb_ = KBASE(t); kreg0 = *(const u32x4*)(K + (kb_ + lane) * 1536 + h * 96 + wid * 8); \
;         if (k2) kreg1 = *(const u32x4*)(K + (kb_ + lane) * 1536 + h * 96 + (8 + wid) * 8); } while (0)
; #define LOADV(t) do { const long kb_ = KBASE(t); vreg = *(const u32x4*)(V + (kb_ + 16 * (wid & 3) + (lane >> 2)) * 1024 + h * 64 + (wid >> 2) * 32 + (lane & 3) * 8); } while (0)
; #define STOREK(s) do { LAS unsigned char* st_ = sh + (s) * STG; *(LAS u32x4*)(st_ + wid * 1024 + lane * 16) = kreg0; if (k2) *(LAS u32x4*)(st_ + (8 + wid) * 1024 + lane * 16) = kreg1; } while (0)
; #define STOREV(s) do { LAS unsigned char* st_ = sh + (s) * STG; *(LAS u32x4*)(st_ + KST + wid * 1024 + lane * 16) = vreg; } while (0)
; DEV void attn_unit(int b, int h, int qb, const bf16_t* Q, const bf16_t* K, const bf16_t* V, bf16_t* O, LAS unsigned char* sh, const int tid, const float* qgain) {
;     ...
;     LOADK(0); LOADV(0); STOREK(0); STOREV(0); LOADK(1); STOREK(1); __syncthreads();
;     f32x16 pA0, pA1, pB0 = f32x16{}, pB1 = f32x16{};
;     QKT(pA0, pA1, 0);
;     { float m0 = pA0[0];
; #pragma unroll
;         for (int r = 0; r < 16; ++r) m0 = max3f(m0, pA0[r], pA1[r]);
;         mrun = fmaxf(m0, __shfl_xor(m0, 32)); }
;     for (int t = 0; t < NT - 2; t += 2) {
;         STEP(pA0, pA1, pB0, pB1, t, true);
;         STEP(pB0, pB1, pA0, pA1, t + 1, true);
;     }
;     STEP(pA0, pA1, pB0, pB1, NT - 2, true);
;     STEP(pB0, pB1, pA0, pA1, NT - 1, false);
.Lat_k2_17:
	s_add_u32 s12, s12, 0x30000
	s_addc_u32 s13, s13, 0
	s_mov_b64 s[14:15], s[38:39]
	s_add_i32 m0, s22, 0x3000
	s_nop 0
	global_load_lds_dwordx4 v145, s[14:15]
	s_add_u32 s14, s14, 0x20000
	s_addc_u32 s15, s15, 0
	ds_read_b128 v[196:199], v126 offset:20480
	ds_read_b128 v[200:203], v126 offset:20992
	ds_read_b128 v[204:207], v126 offset:22528
	ds_read_b128 v[208:211], v126 offset:23040
	ds_read_b128 v[212:215], v126 offset:24576
	ds_read_b128 v[216:219], v126 offset:25088
	ds_read_b64_tr_b16 v[220:221], v127 offset:0
	ds_read_b64_tr_b16 v[222:223], v127 offset:512
	ds_read_b64_tr_b16 v[228:229], v127 offset:4096
	ds_read_b64_tr_b16 v[230:231], v127 offset:4608
	v_max_f32_e32 v149, v48, v49
	v_sub_f32_e32 v48, v48, v174
	v_sub_f32_e32 v49, v49, v174
	v_exp_f32_e32 v48, v48
	v_exp_f32_e32 v49, v49
	v_mov_b32_e32 v176, v48
	v_mov_b32_e32 v177, v49
	v_cvt_pk_bf16_f32 v48, v48, v49
	v_max3_f32 v149, v149, v50, v51
	v_sub_f32_e32 v50, v50, v174
	v_sub_f32_e32 v51, v51, v174
	v_exp_f32_e32 v50, v50
	s_waitcnt lgkmcnt(9)
	v_mfma_f32_32x32x16_bf16 v[80:95], v[196:199], v[110:113], 0
	ds_read_b128 v[196:199], v126 offset:26624
	ds_read_b64_tr_b16 v[224:225], v127 offset:1024
	ds_read_b64_tr_b16 v[226:227], v127 offset:1536
	v_exp_f32_e32 v51, v51
	v_add_f32_e32 v176, v50, v176
	v_add_f32_e32 v177, v51, v177
	v_cvt_pk_bf16_f32 v49, v50, v51
	v_max3_f32 v149, v149, v52, v53
	v_sub_f32_e32 v52, v52, v174
	v_sub_f32_e32 v53, v53, v174
	s_waitcnt lgkmcnt(11)
	v_mfma_f32_32x32x16_bf16 v[64:79], v[200:203], v[110:113], 0
	ds_read_b128 v[200:203], v126 offset:27136
	ds_read_b64_tr_b16 v[232:233], v127 offset:5120
	ds_read_b64_tr_b16 v[234:235], v127 offset:5632
	v_exp_f32_e32 v52, v52
	v_exp_f32_e32 v53, v53
	v_add_f32_e32 v176, v52, v176
	v_add_f32_e32 v177, v53, v177
	v_cvt_pk_bf16_f32 v50, v52, v53
	v_max3_f32 v149, v149, v54, v55
	v_sub_f32_e32 v54, v54, v174
	s_waitcnt lgkmcnt(13)
	v_mfma_f32_32x32x16_bf16 v[80:95], v[204:207], v[106:109], v[80:95]
	ds_read_b128 v[204:207], v126 offset:28672
	v_sub_f32_e32 v55, v55, v174
	v_exp_f32_e32 v54, v54
	v_exp_f32_e32 v55, v55
	v_add_f32_e32 v176, v54, v176
	v_add_f32_e32 v177, v55, v177
	v_cvt_pk_bf16_f32 v51, v54, v55
	v_max3_f32 v149, v149, v56, v57
	s_waitcnt lgkmcnt(13)
	v_mfma_f32_32x32x16_bf16 v[64:79], v[208:211], v[106:109], v[64:79]
	ds_read_b128 v[208:211], v126 offset:29184
	v_sub_f32_e32 v56, v56, v174
	v_sub_f32_e32 v57, v57, v174
	v_exp_f32_e32 v56, v56
	v_exp_f32_e32 v57, v57
	v_add_f32_e32 v176, v56, v176
	v_add_f32_e32 v177, v57, v177
	v_cvt_pk_bf16_f32 v52, v56, v57
	s_waitcnt lgkmcnt(13)
	v_mfma_f32_32x32x16_bf16 v[80:95], v[212:215], v[114:117], v[80:95]
	ds_read_b128 v[212:215], v126 offset:30720
	v_max3_f32 v149, v149, v58, v59
	v_sub_f32_e32 v58, v58, v174
	v_sub_f32_e32 v59, v59, v174
	v_exp_f32_e32 v58, v58
	v_exp_f32_e32 v59, v59
	v_add_f32_e32 v176, v58, v176
	v_add_f32_e32 v177, v59, v177
	s_waitcnt lgkmcnt(11)
	v_mfma_f32_32x32x16_bf16 v[0:15], v[48:51], v[220:223], v[0:15]
	ds_read_b64_tr_b16 v[236:237], v127 offset:2048
	ds_read_b64_tr_b16 v[238:239], v127 offset:2560
	v_cvt_pk_bf16_f32 v53, v58, v59
	v_max3_f32 v149, v149, v60, v61
	v_sub_f32_e32 v60, v60, v174
	v_sub_f32_e32 v61, v61, v174
	v_exp_f32_e32 v60, v60
	v_exp_f32_e32 v61, v61
	v_add_f32_e32 v176, v60, v176
	s_waitcnt lgkmcnt(11)
	v_mfma_f32_32x32x16_bf16 v[16:31], v[48:51], v[228:231], v[16:31]
	ds_read_b64_tr_b16 v[244:245], v127 offset:6144
	ds_read_b64_tr_b16 v[246:247], v127 offset:6656
	v_add_f32_e32 v177, v61, v177
	v_cvt_pk_bf16_f32 v54, v60, v61
	v_max3_f32 v149, v149, v62, v63
	v_sub_f32_e32 v62, v62, v174
	v_sub_f32_e32 v63, v63, v174
	v_exp_f32_e32 v62, v62
	v_exp_f32_e32 v63, v63
	v_mfma_f32_32x32x16_bf16 v[64:79], v[216:219], v[114:117], v[64:79]
	ds_read_b128 v[216:219], v126 offset:31232
	v_add_f32_e32 v176, v62, v176
	v_add_f32_e32 v177, v63, v177
	v_cvt_pk_bf16_f32 v55, v62, v63
	v_max3_f32 v149, v149, v32, v33
	v_sub_f32_e32 v32, v32, v174
	v_sub_f32_e32 v33, v33, v174
	v_exp_f32_e32 v32, v32
	s_waitcnt lgkmcnt(13)
	v_mfma_f32_32x32x16_bf16 v[80:95], v[196:199], v[118:121], v[80:95]
	v_exp_f32_e32 v33, v33
	v_add_f32_e32 v176, v32, v176
	v_add_f32_e32 v177, v33, v177
	v_cvt_pk_bf16_f32 v32, v32, v33
	v_max3_f32 v149, v149, v34, v35
	v_sub_f32_e32 v34, v34, v174
	v_sub_f32_e32 v35, v35, v174
	s_waitcnt lgkmcnt(10)
	v_mfma_f32_32x32x16_bf16 v[64:79], v[200:203], v[118:121], v[64:79]
	v_exp_f32_e32 v34, v34
	v_exp_f32_e32 v35, v35
	v_add_f32_e32 v176, v34, v176
	v_add_f32_e32 v177, v35, v177
	v_cvt_pk_bf16_f32 v33, v34, v35
	v_max3_f32 v149, v149, v36, v37
	v_sub_f32_e32 v36, v36, v174
	v_mfma_f32_32x32x16_bf16 v[0:15], v[52:55], v[224:227], v[0:15]
	ds_read_b64_tr_b16 v[240:241], v127 offset:3072
	ds_read_b64_tr_b16 v[242:243], v127 offset:3584
	v_sub_f32_e32 v37, v37, v174
	v_exp_f32_e32 v36, v36
	v_exp_f32_e32 v37, v37
	v_add_f32_e32 v176, v36, v176
	v_add_f32_e32 v177, v37, v177
	v_cvt_pk_bf16_f32 v34, v36, v37
	v_max3_f32 v149, v149, v38, v39
	s_waitcnt lgkmcnt(10)
	v_mfma_f32_32x32x16_bf16 v[16:31], v[52:55], v[232:235], v[16:31]
	ds_read_b64_tr_b16 v[122:123], v127 offset:7168
	ds_read_b64_tr_b16 v[124:125], v127 offset:7680
	v_sub_f32_e32 v38, v38, v174
	v_sub_f32_e32 v39, v39, v174
	v_exp_f32_e32 v38, v38
	v_exp_f32_e32 v39, v39
	v_add_f32_e32 v176, v38, v176
	v_add_f32_e32 v177, v39, v177
	v_cvt_pk_bf16_f32 v35, v38, v39
	s_waitcnt lgkmcnt(11)
	v_mfma_f32_32x32x16_bf16 v[80:95], v[204:207], v[102:105], v[80:95]
	v_max3_f32 v149, v149, v40, v41
	v_sub_f32_e32 v40, v40, v174
	v_sub_f32_e32 v41, v41, v174
	v_exp_f32_e32 v40, v40
	v_exp_f32_e32 v41, v41
	v_add_f32_e32 v176, v40, v176
	v_add_f32_e32 v177, v41, v177
	s_waitcnt lgkmcnt(10)
	v_mfma_f32_32x32x16_bf16 v[64:79], v[208:211], v[102:105], v[64:79]
	v_cvt_pk_bf16_f32 v36, v40, v41
	v_max3_f32 v149, v149, v42, v43
	v_sub_f32_e32 v42, v42, v174
	v_sub_f32_e32 v43, v43, v174
	v_exp_f32_e32 v42, v42
	v_exp_f32_e32 v43, v43
	v_add_f32_e32 v176, v42, v176
	s_waitcnt lgkmcnt(7)
	v_mfma_f32_32x32x16_bf16 v[0:15], v[32:35], v[236:239], v[0:15]
	v_add_f32_e32 v177, v43, v177
	v_cvt_pk_bf16_f32 v37, v42, v43
	v_max3_f32 v149, v149, v44, v45
	v_sub_f32_e32 v44, v44, v174
	v_sub_f32_e32 v45, v45, v174
	v_exp_f32_e32 v44, v44
	v_exp_f32_e32 v45, v45
	s_waitcnt lgkmcnt(5)
	v_mfma_f32_32x32x16_bf16 v[16:31], v[32:35], v[244:247], v[16:31]
	v_add_f32_e32 v176, v44, v176
	v_add_f32_e32 v177, v45, v177
	v_cvt_pk_bf16_f32 v38, v44, v45
	v_max3_f32 v149, v149, v46, v47
	v_sub_f32_e32 v46, v46, v174
	v_sub_f32_e32 v47, v47, v174
	v_exp_f32_e32 v46, v46
	v_mfma_f32_32x32x16_bf16 v[80:95], v[212:215], v[98:101], v[80:95]
	v_exp_f32_e32 v47, v47
	v_add_f32_e32 v176, v46, v176
	v_add_f32_e32 v177, v47, v177
	v_cvt_pk_bf16_f32 v39, v46, v47
	v_add_f32_e32 v179, v176, v177
	v_mov_b32_e32 v175, v149
	v_mov_b32_e32 v178, v149
	s_waitcnt lgkmcnt(4)
	v_mfma_f32_32x32x16_bf16 v[64:79], v[216:219], v[98:101], v[64:79]
	v_add_f32_e32 v147, v147, v179
	s_nop 1
	v_permlane32_swap_b32_e32 v175, v178
	v_max_f32_e32 v175, v175, v178
	v_sub_f32_e32 v175, v175, v174
	v_cmp_lt_f32_e32 vcc, s43, v175
	s_waitcnt lgkmcnt(2)
	v_mfma_f32_32x32x16_bf16 v[0:15], v[36:39], v[240:243], v[0:15]
	s_waitcnt lgkmcnt(0)
	v_mfma_f32_32x32x16_bf16 v[16:31], v[36:39], v[122:125], v[16:31]
	s_cbranch_vccz .Lat_nr_18
	v_max_f32_e32 v175, v175, v175
	v_max_f32_e32 v175, 0, v175
	v_exp_f32_e64 v178, -v175
	s_and_saveexec_b64 s[4:5], s[2:3]
	ds_write_b32 v143, v178 offset:40960
	s_or_b64 exec, exec, s[4:5]
	s_waitcnt lgkmcnt(0)
	v_add_u32_e32 v179, s33, v191
	v_add_f32_e32 v174, v174, v175
	v_mul_f32_e32 v147, v147, v178
	ds_read_b128 v[196:199], v179 offset:40960
	ds_read_b128 v[200:203], v179 offset:40992
	ds_read_b128 v[204:207], v179 offset:41024
	ds_read_b128 v[208:211], v179 offset:41056
	s_waitcnt lgkmcnt(0)
	s_nop 15
	v_pk_mul_f32 v[0:1], v[0:1], v[196:197]
	v_pk_mul_f32 v[2:3], v[2:3], v[198:199]
	v_pk_mul_f32 v[4:5], v[4:5], v[200:201]
	v_pk_mul_f32 v[6:7], v[6:7], v[202:203]
	v_pk_mul_f32 v[8:9], v[8:9], v[204:205]
	v_pk_mul_f32 v[10:11], v[10:11], v[206:207]
	v_pk_mul_f32 v[12:13], v[12:13], v[208:209]
	v_pk_mul_f32 v[14:15], v[14:15], v[210:211]
	v_pk_mul_f32 v[16:17], v[16:17], v[196:197]
	v_pk_mul_f32 v[18:19], v[18:19], v[198:199]
	v_pk_mul_f32 v[20:21], v[20:21], v[200:201]
	v_pk_mul_f32 v[22:23], v[22:23], v[202:203]
	v_pk_mul_f32 v[24:25], v[24:25], v[204:205]
	v_pk_mul_f32 v[26:27], v[26:27], v[206:207]
	v_pk_mul_f32 v[28:29], v[28:29], v[208:209]
	v_pk_mul_f32 v[30:31], v[30:31], v[210:211]

.Lat_nr_20:
	s_waitcnt vmcnt(2)
	s_barrier
	s_add_i32 m0, s22, 0x15000
	s_cmp_eq_u32 s23, 0
	global_load_lds_dwordx4 v128, s[12:13]
	s_cbranch_scc1 .Lat_k2_21
	s_add_i32 m0, s22, 0x17000
	s_nop 0
	global_load_lds_dwordx4 v129, s[12:13]

.Lat_nr_22:
	s_waitcnt vmcnt(2)
	s_barrier
	s_add_i32 m0, s22, 0x18000
	s_nop 0
	global_load_lds_dwordx4 v145, s[14:15]
	ds_read_b128 v[196:199], v126 offset:0
	ds_read_b128 v[200:203], v126 offset:512
	ds_read_b128 v[204:207], v126 offset:2048
	ds_read_b128 v[208:211], v126 offset:2560
	ds_read_b128 v[212:215], v126 offset:4096
	ds_read_b128 v[216:219], v126 offset:4608
	ds_read_b64_tr_b16 v[220:221], v139 offset:20480
	ds_read_b64_tr_b16 v[222:223], v139 offset:20992
	ds_read_b64_tr_b16 v[228:229], v139 offset:24576
	ds_read_b64_tr_b16 v[230:231], v139 offset:25088
	v_max_f32_e32 v149, v80, v81
	v_sub_f32_e32 v80, v80, v174
	v_sub_f32_e32 v81, v81, v174
	v_exp_f32_e32 v80, v80
	v_exp_f32_e32 v81, v81
	v_mov_b32_e32 v176, v80
	v_mov_b32_e32 v177, v81
	v_cvt_pk_bf16_f32 v80, v80, v81
	v_max3_f32 v149, v149, v82, v83
	v_sub_f32_e32 v82, v82, v174
	v_sub_f32_e32 v83, v83, v174
	v_exp_f32_e32 v82, v82
	s_waitcnt lgkmcnt(9)
	v_mfma_f32_32x32x16_bf16 v[48:63], v[196:199], v[110:113], 0
	ds_read_b128 v[196:199], v126 offset:6144
	ds_read_b64_tr_b16 v[224:225], v139 offset:21504
	ds_read_b64_tr_b16 v[226:227], v139 offset:22016
	v_exp_f32_e32 v83, v83
	v_add_f32_e32 v176, v82, v176
	v_add_f32_e32 v177, v83, v177
	v_cvt_pk_bf16_f32 v81, v82, v83
	v_max3_f32 v149, v149, v84, v85
	v_sub_f32_e32 v84, v84, v174
	v_sub_f32_e32 v85, v85, v174
	s_waitcnt lgkmcnt(11)
	v_mfma_f32_32x32x16_bf16 v[32:47], v[200:203], v[110:113], 0
	ds_read_b128 v[200:203], v126 offset:6656
	ds_read_b64_tr_b16 v[232:233], v139 offset:25600
	ds_read_b64_tr_b16 v[234:235], v139 offset:26112
	v_exp_f32_e32 v84, v84
	v_exp_f32_e32 v85, v85
	v_add_f32_e32 v176, v84, v176
	v_add_f32_e32 v177, v85, v177
	v_cvt_pk_bf16_f32 v82, v84, v85
	v_max3_f32 v149, v149, v86, v87
	v_sub_f32_e32 v86, v86, v174
	s_waitcnt lgkmcnt(13)
	v_mfma_f32_32x32x16_bf16 v[48:63], v[204:207], v[106:109], v[48:63]
	ds_read_b128 v[204:207], v126 offset:8192
	v_sub_f32_e32 v87, v87, v174
	v_exp_f32_e32 v86, v86
	v_exp_f32_e32 v87, v87
	v_add_f32_e32 v176, v86, v176
	v_add_f32_e32 v177, v87, v177
	v_cvt_pk_bf16_f32 v83, v86, v87
	v_max3_f32 v149, v149, v88, v89
	s_waitcnt lgkmcnt(13)
	v_mfma_f32_32x32x16_bf16 v[32:47], v[208:211], v[106:109], v[32:47]
	ds_read_b128 v[208:211], v126 offset:8704
	v_sub_f32_e32 v88, v88, v174
	v_sub_f32_e32 v89, v89, v174
	v_exp_f32_e32 v88, v88
	v_exp_f32_e32 v89, v89
	v_add_f32_e32 v176, v88, v176
	v_add_f32_e32 v177, v89, v177
	v_cvt_pk_bf16_f32 v84, v88, v89
	s_waitcnt lgkmcnt(13)
	v_mfma_f32_32x32x16_bf16 v[48:63], v[212:215], v[114:117], v[48:63]
	ds_read_b128 v[212:215], v126 offset:10240
	v_max3_f32 v149, v149, v90, v91
	v_sub_f32_e32 v90, v90, v174
	v_sub_f32_e32 v91, v91, v174
	v_exp_f32_e32 v90, v90
	v_exp_f32_e32 v91, v91
	v_add_f32_e32 v176, v90, v176
	v_add_f32_e32 v177, v91, v177
	s_waitcnt lgkmcnt(11)
	v_mfma_f32_32x32x16_bf16 v[0:15], v[80:83], v[220:223], v[0:15]
	ds_read_b64_tr_b16 v[236:237], v139 offset:22528
	ds_read_b64_tr_b16 v[238:239], v139 offset:23040
	v_cvt_pk_bf16_f32 v85, v90, v91
	v_max3_f32 v149, v149, v92, v93
	v_sub_f32_e32 v92, v92, v174
	v_sub_f32_e32 v93, v93, v174
	v_exp_f32_e32 v92, v92
	v_exp_f32_e32 v93, v93
	v_add_f32_e32 v176, v92, v176
	s_waitcnt lgkmcnt(11)
	v_mfma_f32_32x32x16_bf16 v[16:31], v[80:83], v[228:231], v[16:31]
	ds_read_b64_tr_b16 v[244:245], v139 offset:26624
	ds_read_b64_tr_b16 v[246:247], v139 offset:27136
	v_add_f32_e32 v177, v93, v177
	v_cvt_pk_bf16_f32 v86, v92, v93
	v_max3_f32 v149, v149, v94, v95
	v_sub_f32_e32 v94, v94, v174
	v_sub_f32_e32 v95, v95, v174
	v_exp_f32_e32 v94, v94
	v_exp_f32_e32 v95, v95
	v_mfma_f32_32x32x16_bf16 v[32:47], v[216:219], v[114:117], v[32:47]
	ds_read_b128 v[216:219], v126 offset:10752
	v_add_f32_e32 v176, v94, v176
	v_add_f32_e32 v177, v95, v177
	v_cvt_pk_bf16_f32 v87, v94, v95
	v_max3_f32 v149, v149, v64, v65
	v_sub_f32_e32 v64, v64, v174
	v_sub_f32_e32 v65, v65, v174
	v_exp_f32_e32 v64, v64
	s_waitcnt lgkmcnt(13)
	v_mfma_f32_32x32x16_bf16 v[48:63], v[196:199], v[118:121], v[48:63]
	v_exp_f32_e32 v65, v65
	v_add_f32_e32 v176, v64, v176
	v_add_f32_e32 v177, v65, v177
	v_cvt_pk_bf16_f32 v64, v64, v65
	v_max3_f32 v149, v149, v66, v67
	v_sub_f32_e32 v66, v66, v174
	v_sub_f32_e32 v67, v67, v174
	s_waitcnt lgkmcnt(10)
	v_mfma_f32_32x32x16_bf16 v[32:47], v[200:203], v[118:121], v[32:47]
	v_exp_f32_e32 v66, v66
	v_exp_f32_e32 v67, v67
	v_add_f32_e32 v176, v66, v176
	v_add_f32_e32 v177, v67, v177
	v_cvt_pk_bf16_f32 v65, v66, v67
	v_max3_f32 v149, v149, v68, v69
	v_sub_f32_e32 v68, v68, v174
	v_mfma_f32_32x32x16_bf16 v[0:15], v[84:87], v[224:227], v[0:15]
	ds_read_b64_tr_b16 v[240:241], v139 offset:23552
	ds_read_b64_tr_b16 v[242:243], v139 offset:24064
	v_sub_f32_e32 v69, v69, v174
	v_exp_f32_e32 v68, v68
	v_exp_f32_e32 v69, v69
	v_add_f32_e32 v176, v68, v176
	v_add_f32_e32 v177, v69, v177
	v_cvt_pk_bf16_f32 v66, v68, v69
	v_max3_f32 v149, v149, v70, v71
	s_waitcnt lgkmcnt(10)
	v_mfma_f32_32x32x16_bf16 v[16:31], v[84:87], v[232:235], v[16:31]
	ds_read_b64_tr_b16 v[122:123], v139 offset:27648
	ds_read_b64_tr_b16 v[124:125], v139 offset:28160
	v_sub_f32_e32 v70, v70, v174
	v_sub_f32_e32 v71, v71, v174
	v_exp_f32_e32 v70, v70
	v_exp_f32_e32 v71, v71
	v_add_f32_e32 v176, v70, v176
	v_add_f32_e32 v177, v71, v177
	v_cvt_pk_bf16_f32 v67, v70, v71
	s_waitcnt lgkmcnt(11)
	v_mfma_f32_32x32x16_bf16 v[48:63], v[204:207], v[102:105], v[48:63]
	v_max3_f32 v149, v149, v72, v73
	v_sub_f32_e32 v72, v72, v174
	v_sub_f32_e32 v73, v73, v174
	v_exp_f32_e32 v72, v72
	v_exp_f32_e32 v73, v73
	v_add_f32_e32 v176, v72, v176
	v_add_f32_e32 v177, v73, v177
	s_waitcnt lgkmcnt(10)
; DEV float max3f(float a, float b, float c) { return fmaxf(fmaxf(a, b), c); }
; #define LOADK(t) do { const long kb_ = KBASE(t); kreg0 = *(const u32x4*)(K + (kb_ + lane) * 1536 + h * 96 + wid * 8); \
;         if (k2) kreg1 = *(const u32x4*)(K + (kb_ + lane) * 1536 + h * 96 + (8 + wid) * 8); } while (0)
; #define LOADV(t) do { const long kb_ = KBASE(t); vreg = *(const u32x4*)(V + (kb_ + 16 * (wid & 3) + (lane >> 2)) * 1024 + h * 64 + (wid >> 2) * 32 + (lane & 3) * 8); } while (0)
; #define STOREK(s) do { LAS unsigned char* st_ = sh + (s) * STG; *(LAS u32x4*)(st_ + wid * 1024 + lane * 16) = kreg0; if (k2) *(LAS u32x4*)(st_ + (8 + wid) * 1024 + lane * 16) = kreg1; } while (0)
; #define STOREV(s) do { LAS unsigned char* st_ = sh + (s) * STG; *(LAS u32x4*)(st_ + KST + wid * 1024 + lane * 16) = vreg; } while (0)
; DEV void attn_unit(int b, int h, int qb, const bf16_t* Q, const bf16_t* K, const bf16_t* V, bf16_t* O, LAS unsigned char* sh, const int tid, const float* qgain) {
;     ...
;     LOADK(0); LOADV(0); STOREK(0); STOREV(0); LOADK(1); STOREK(1); __syncthreads();
;     f32x16 pA0, pA1, pB0 = f32x16{}, pB1 = f32x16{};
;     QKT(pA0, pA1, 0);
;     { float m0 = pA0[0];
; #pragma unroll
;         for (int r = 0; r < 16; ++r) m0 = max3f(m0, pA0[r], pA1[r]);
;         mrun = fmaxf(m0, __shfl_xor(m0, 32)); }
;     for (int t = 0; t < NT - 2; t += 2) {
;         STEP(pA0, pA1, pB0, pB1, t, true);
;         STEP(pB0, pB1, pA0, pA1, t + 1, true);
;     }
;     STEP(pA0, pA1, pB0, pB1, NT - 2, true);
;     STEP(pB0, pB1, pA0, pA1, NT - 1, false);
	v_mfma_f32_32x32x16_bf16 v[32:47], v[208:211], v[102:105], v[32:47]
	v_cvt_pk_bf16_f32 v68, v72, v73
	v_max3_f32 v149, v149, v74, v75
	v_sub_f32_e32 v74, v74, v174
	v_sub_f32_e32 v75, v75, v174
	v_exp_f32_e32 v74, v74
	v_exp_f32_e32 v75, v75
	v_add_f32_e32 v176, v74, v176
	s_waitcnt lgkmcnt(7)
	v_mfma_f32_32x32x16_bf16 v[0:15], v[64:67], v[236:239], v[0:15]
	v_add_f32_e32 v177, v75, v177
	v_cvt_pk_bf16_f32 v69, v74, v75
	v_max3_f32 v149, v149, v76, v77
	v_sub_f32_e32 v76, v76, v174
	v_sub_f32_e32 v77, v77, v174
	v_exp_f32_e32 v76, v76
	v_exp_f32_e32 v77, v77
	s_waitcnt lgkmcnt(5)
	v_mfma_f32_32x32x16_bf16 v[16:31], v[64:67], v[244:247], v[16:31]
	v_add_f32_e32 v176, v76, v176
	v_add_f32_e32 v177, v77, v177
	v_cvt_pk_bf16_f32 v70, v76, v77
	v_max3_f32 v149, v149, v78, v79
	v_sub_f32_e32 v78, v78, v174
	v_sub_f32_e32 v79, v79, v174
	v_exp_f32_e32 v78, v78
	v_mfma_f32_32x32x16_bf16 v[48:63], v[212:215], v[98:101], v[48:63]
	v_exp_f32_e32 v79, v79
	v_add_f32_e32 v176, v78, v176
	v_add_f32_e32 v177, v79, v177
	v_cvt_pk_bf16_f32 v71, v78, v79
	v_add_f32_e32 v179, v176, v177
	v_mov_b32_e32 v175, v149
	v_mov_b32_e32 v178, v149
	s_waitcnt lgkmcnt(4)
	v_mfma_f32_32x32x16_bf16 v[32:47], v[216:219], v[98:101], v[32:47]
	v_add_f32_e32 v147, v147, v179
	s_nop 1
	v_permlane32_swap_b32_e32 v175, v178
	v_max_f32_e32 v175, v175, v178
	v_sub_f32_e32 v175, v175, v174
	v_cmp_lt_f32_e32 vcc, s43, v175
	s_waitcnt lgkmcnt(2)
	v_mfma_f32_32x32x16_bf16 v[0:15], v[68:71], v[240:243], v[0:15]
	s_waitcnt lgkmcnt(0)
	v_mfma_f32_32x32x16_bf16 v[16:31], v[68:71], v[122:125], v[16:31]
	s_cbranch_vccz .Lat_nr_23
	v_max_f32_e32 v175, v175, v175
	v_max_f32_e32 v175, 0, v175
	v_exp_f32_e64 v178, -v175
	s_and_saveexec_b64 s[4:5], s[2:3]
	ds_write_b32 v143, v178 offset:40960
	s_or_b64 exec, exec, s[4:5]
	s_waitcnt lgkmcnt(0)
	v_add_u32_e32 v179, s33, v191
	v_add_f32_e32 v174, v174, v175
	v_mul_f32_e32 v147, v147, v178
	ds_read_b128 v[196:199], v179 offset:40960
	ds_read_b128 v[200:203], v179 offset:40992
	ds_read_b128 v[204:207], v179 offset:41024
	ds_read_b128 v[208:211], v179 offset:41056
	s_waitcnt lgkmcnt(0)
	s_nop 15
	v_pk_mul_f32 v[0:1], v[0:1], v[196:197]
	v_pk_mul_f32 v[2:3], v[2:3], v[198:199]
	v_pk_mul_f32 v[4:5], v[4:5], v[200:201]
	v_pk_mul_f32 v[6:7], v[6:7], v[202:203]
	v_pk_mul_f32 v[8:9], v[8:9], v[204:205]
	v_pk_mul_f32 v[10:11], v[10:11], v[206:207]
	v_pk_mul_f32 v[12:13], v[12:13], v[208:209]
	v_pk_mul_f32 v[14:15], v[14:15], v[210:211]
	v_pk_mul_f32 v[16:17], v[16:17], v[196:197]
	v_pk_mul_f32 v[18:19], v[18:19], v[198:199]
	v_pk_mul_f32 v[20:21], v[20:21], v[200:201]
	v_pk_mul_f32 v[22:23], v[22:23], v[202:203]
	v_pk_mul_f32 v[24:25], v[24:25], v[204:205]
	v_pk_mul_f32 v[26:27], v[26:27], v[206:207]
	v_pk_mul_f32 v[28:29], v[28:29], v[208:209]
	v_pk_mul_f32 v[30:31], v[30:31], v[210:211]
.Lat_nr_23:
	s_waitcnt vmcnt(1)
	s_barrier
	ds_read_b128 v[196:199], v126 offset:20480
	ds_read_b128 v[200:203], v126 offset:20992
	ds_read_b128 v[204:207], v126 offset:22528
	ds_read_b128 v[208:211], v126 offset:23040
	ds_read_b128 v[212:215], v126 offset:24576
	ds_read_b128 v[216:219], v126 offset:25088
	ds_read_b64_tr_b16 v[220:221], v127 offset:0
	ds_read_b64_tr_b16 v[222:223], v127 offset:512
	ds_read_b64_tr_b16 v[228:229], v127 offset:4096
	ds_read_b64_tr_b16 v[230:231], v127 offset:4608
	v_max_f32_e32 v149, v48, v49
	v_sub_f32_e32 v48, v48, v174
	v_sub_f32_e32 v49, v49, v174
	v_exp_f32_e32 v48, v48
	v_exp_f32_e32 v49, v49
	v_mov_b32_e32 v176, v48
	v_mov_b32_e32 v177, v49
	v_cvt_pk_bf16_f32 v48, v48, v49
	v_max3_f32 v149, v149, v50, v51
	v_sub_f32_e32 v50, v50, v174
	v_sub_f32_e32 v51, v51, v174
	v_exp_f32_e32 v50, v50
	s_waitcnt lgkmcnt(9)
	v_mfma_f32_32x32x16_bf16 v[80:95], v[196:199], v[110:113], 0
	ds_read_b128 v[196:199], v126 offset:26624
	ds_read_b64_tr_b16 v[224:225], v127 offset:1024
	ds_read_b64_tr_b16 v[226:227], v127 offset:1536
	v_exp_f32_e32 v51, v51
	v_add_f32_e32 v176, v50, v176
	v_add_f32_e32 v177, v51, v177
	v_cvt_pk_bf16_f32 v49, v50, v51
	v_max3_f32 v149, v149, v52, v53
	v_sub_f32_e32 v52, v52, v174
	v_sub_f32_e32 v53, v53, v174
	s_waitcnt lgkmcnt(11)
	v_mfma_f32_32x32x16_bf16 v[64:79], v[200:203], v[110:113], 0
	ds_read_b128 v[200:203], v126 offset:27136
	ds_read_b64_tr_b16 v[232:233], v127 offset:5120
	ds_read_b64_tr_b16 v[234:235], v127 offset:5632
	v_exp_f32_e32 v52, v52
	v_exp_f32_e32 v53, v53
	v_add_f32_e32 v176, v52, v176
	v_add_f32_e32 v177, v53, v177
	v_cvt_pk_bf16_f32 v50, v52, v53
	v_max3_f32 v149, v149, v54, v55
	v_sub_f32_e32 v54, v54, v174
	s_waitcnt lgkmcnt(13)
	v_mfma_f32_32x32x16_bf16 v[80:95], v[204:207], v[106:109], v[80:95]
	ds_read_b128 v[204:207], v126 offset:28672
	v_sub_f32_e32 v55, v55, v174
	v_exp_f32_e32 v54, v54
	v_exp_f32_e32 v55, v55
	v_add_f32_e32 v176, v54, v176
	v_add_f32_e32 v177, v55, v177
	v_cvt_pk_bf16_f32 v51, v54, v55
	v_max3_f32 v149, v149, v56, v57
	s_waitcnt lgkmcnt(13)
	v_mfma_f32_32x32x16_bf16 v[64:79], v[208:211], v[106:109], v[64:79]
	ds_read_b128 v[208:211], v126 offset:29184
	v_sub_f32_e32 v56, v56, v174
	v_sub_f32_e32 v57, v57, v174
	v_exp_f32_e32 v56, v56
	v_exp_f32_e32 v57, v57
	v_add_f32_e32 v176, v56, v176
	v_add_f32_e32 v177, v57, v177
	v_cvt_pk_bf16_f32 v52, v56, v57
	s_waitcnt lgkmcnt(13)
	v_mfma_f32_32x32x16_bf16 v[80:95], v[212:215], v[114:117], v[80:95]
	ds_read_b128 v[212:215], v126 offset:30720
	v_max3_f32 v149, v149, v58, v59
	v_sub_f32_e32 v58, v58, v174
	v_sub_f32_e32 v59, v59, v174
	v_exp_f32_e32 v58, v58
	v_exp_f32_e32 v59, v59
	v_add_f32_e32 v176, v58, v176
	v_add_f32_e32 v177, v59, v177
	s_waitcnt lgkmcnt(11)
	v_mfma_f32_32x32x16_bf16 v[0:15], v[48:51], v[220:223], v[0:15]
	ds_read_b64_tr_b16 v[236:237], v127 offset:2048
	ds_read_b64_tr_b16 v[238:239], v127 offset:2560
	v_cvt_pk_bf16_f32 v53, v58, v59
	v_max3_f32 v149, v149, v60, v61
	v_sub_f32_e32 v60, v60, v174
	v_sub_f32_e32 v61, v61, v174
	v_exp_f32_e32 v60, v60
	v_exp_f32_e32 v61, v61
	v_add_f32_e32 v176, v60, v176
	s_waitcnt lgkmcnt(11)
	v_mfma_f32_32x32x16_bf16 v[16:31], v[48:51], v[228:231], v[16:31]
	ds_read_b64_tr_b16 v[244:245], v127 offset:6144
	ds_read_b64_tr_b16 v[246:247], v127 offset:6656
	v_add_f32_e32 v177, v61, v177
	v_cvt_pk_bf16_f32 v54, v60, v61
	v_max3_f32 v149, v149, v62, v63
	v_sub_f32_e32 v62, v62, v174
	v_sub_f32_e32 v63, v63, v174
	v_exp_f32_e32 v62, v62
	v_exp_f32_e32 v63, v63
	v_mfma_f32_32x32x16_bf16 v[64:79], v[216:219], v[114:117], v[64:79]
	ds_read_b128 v[216:219], v126 offset:31232
	v_add_f32_e32 v176, v62, v176
	v_add_f32_e32 v177, v63, v177
	v_cvt_pk_bf16_f32 v55, v62, v63
	v_max3_f32 v149, v149, v32, v33
	v_sub_f32_e32 v32, v32, v174
	v_sub_f32_e32 v33, v33, v174
	v_exp_f32_e32 v32, v32
	s_waitcnt lgkmcnt(13)
	v_mfma_f32_32x32x16_bf16 v[80:95], v[196:199], v[118:121], v[80:95]
	v_exp_f32_e32 v33, v33
	v_add_f32_e32 v176, v32, v176
	v_add_f32_e32 v177, v33, v177
	v_cvt_pk_bf16_f32 v32, v32, v33
	v_max3_f32 v149, v149, v34, v35
	v_sub_f32_e32 v34, v34, v174
	v_sub_f32_e32 v35, v35, v174
	s_waitcnt lgkmcnt(10)
	v_mfma_f32_32x32x16_bf16 v[64:79], v[200:203], v[118:121], v[64:79]
	v_exp_f32_e32 v34, v34
	v_exp_f32_e32 v35, v35
	v_add_f32_e32 v176, v34, v176
	v_add_f32_e32 v177, v35, v177
	v_cvt_pk_bf16_f32 v33, v34, v35
	v_max3_f32 v149, v149, v36, v37
	v_sub_f32_e32 v36, v36, v174
	v_mfma_f32_32x32x16_bf16 v[0:15], v[52:55], v[224:227], v[0:15]
	ds_read_b64_tr_b16 v[240:241], v127 offset:3072
	ds_read_b64_tr_b16 v[242:243], v127 offset:3584
	v_sub_f32_e32 v37, v37, v174
	v_exp_f32_e32 v36, v36
	v_exp_f32_e32 v37, v37
	v_add_f32_e32 v176, v36, v176
	v_add_f32_e32 v177, v37, v177
	v_cvt_pk_bf16_f32 v34, v36, v37
	v_max3_f32 v149, v149, v38, v39
	s_waitcnt lgkmcnt(10)
	v_mfma_f32_32x32x16_bf16 v[16:31], v[52:55], v[232:235], v[16:31]
	ds_read_b64_tr_b16 v[122:123], v127 offset:7168
	ds_read_b64_tr_b16 v[124:125], v127 offset:7680
	v_sub_f32_e32 v38, v38, v174
	v_sub_f32_e32 v39, v39, v174
	v_exp_f32_e32 v38, v38
	v_exp_f32_e32 v39, v39
	v_add_f32_e32 v176, v38, v176
	v_add_f32_e32 v177, v39, v177
	v_cvt_pk_bf16_f32 v35, v38, v39
	s_waitcnt lgkmcnt(11)
	v_mfma_f32_32x32x16_bf16 v[80:95], v[204:207], v[102:105], v[80:95]
	v_max3_f32 v149, v149, v40, v41
	v_sub_f32_e32 v40, v40, v174
	v_sub_f32_e32 v41, v41, v174
	v_exp_f32_e32 v40, v40
	v_exp_f32_e32 v41, v41
	v_add_f32_e32 v176, v40, v176
	v_add_f32_e32 v177, v41, v177
	s_waitcnt lgkmcnt(10)
	v_mfma_f32_32x32x16_bf16 v[64:79], v[208:211], v[102:105], v[64:79]
	v_cvt_pk_bf16_f32 v36, v40, v41
	v_max3_f32 v149, v149, v42, v43
	v_sub_f32_e32 v42, v42, v174
	v_sub_f32_e32 v43, v43, v174
	v_exp_f32_e32 v42, v42
	v_exp_f32_e32 v43, v43
	v_add_f32_e32 v176, v42, v176
	s_waitcnt lgkmcnt(7)
	v_mfma_f32_32x32x16_bf16 v[0:15], v[32:35], v[236:239], v[0:15]
	v_add_f32_e32 v177, v43, v177
	v_cvt_pk_bf16_f32 v37, v42, v43
	v_max3_f32 v149, v149, v44, v45
	v_sub_f32_e32 v44, v44, v174
	v_sub_f32_e32 v45, v45, v174
	v_exp_f32_e32 v44, v44
	v_exp_f32_e32 v45, v45
	s_waitcnt lgkmcnt(5)
	v_mfma_f32_32x32x16_bf16 v[16:31], v[32:35], v[244:247], v[16:31]
	v_add_f32_e32 v176, v44, v176
	v_add_f32_e32 v177, v45, v177
	v_cvt_pk_bf16_f32 v38, v44, v45
	v_max3_f32 v149, v149, v46, v47
	v_sub_f32_e32 v46, v46, v174
	v_sub_f32_e32 v47, v47, v174
	v_exp_f32_e32 v46, v46
	v_mfma_f32_32x32x16_bf16 v[80:95], v[212:215], v[98:101], v[80:95]
	v_exp_f32_e32 v47, v47
	v_add_f32_e32 v176, v46, v176
	v_add_f32_e32 v177, v47, v177
	v_cvt_pk_bf16_f32 v39, v46, v47
	v_add_f32_e32 v179, v176, v177
	v_mov_b32_e32 v175, v149
	v_mov_b32_e32 v178, v149
	s_waitcnt lgkmcnt(4)
	v_mfma_f32_32x32x16_bf16 v[64:79], v[216:219], v[98:101], v[64:79]
	v_add_f32_e32 v147, v147, v179
	s_nop 1
	v_permlane32_swap_b32_e32 v175, v178
	v_max_f32_e32 v175, v175, v178
	v_sub_f32_e32 v175, v175, v174
	v_cmp_lt_f32_e32 vcc, s43, v175
	s_waitcnt lgkmcnt(2)
	v_mfma_f32_32x32x16_bf16 v[0:15], v[36:39], v[240:243], v[0:15]
	s_waitcnt lgkmcnt(0)
	v_mfma_f32_32x32x16_bf16 v[16:31], v[36:39], v[122:125], v[16:31]
	s_cbranch_vccz .Lat_nr_24
	v_max_f32_e32 v175, v175, v175
	v_max_f32_e32 v175, 0, v175
	v_exp_f32_e64 v178, -v175
	s_and_saveexec_b64 s[4:5], s[2:3]
	ds_write_b32 v143, v178 offset:40960
	s_or_b64 exec, exec, s[4:5]
	s_waitcnt lgkmcnt(0)
	v_add_u32_e32 v179, s33, v191
	v_add_f32_e32 v174, v174, v175
	v_mul_f32_e32 v147, v147, v178
	ds_read_b128 v[196:199], v179 offset:40960
	ds_read_b128 v[200:203], v179 offset:40992
	ds_read_b128 v[204:207], v179 offset:41024
	ds_read_b128 v[208:211], v179 offset:41056
	s_waitcnt lgkmcnt(0)
	s_nop 15
	v_pk_mul_f32 v[0:1], v[0:1], v[196:197]
	v_pk_mul_f32 v[2:3], v[2:3], v[198:199]
	v_pk_mul_f32 v[4:5], v[4:5], v[200:201]
	v_pk_mul_f32 v[6:7], v[6:7], v[202:203]
	v_pk_mul_f32 v[8:9], v[8:9], v[204:205]
	v_pk_mul_f32 v[10:11], v[10:11], v[206:207]
	v_pk_mul_f32 v[12:13], v[12:13], v[208:209]
	v_pk_mul_f32 v[14:15], v[14:15], v[210:211]
	v_pk_mul_f32 v[16:17], v[16:17], v[196:197]
	v_pk_mul_f32 v[18:19], v[18:19], v[198:199]
	v_pk_mul_f32 v[20:21], v[20:21], v[200:201]
	v_pk_mul_f32 v[22:23], v[22:23], v[202:203]
	v_pk_mul_f32 v[24:25], v[24:25], v[204:205]
	v_pk_mul_f32 v[26:27], v[26:27], v[206:207]
	v_pk_mul_f32 v[28:29], v[28:29], v[208:209]
	v_pk_mul_f32 v[30:31], v[30:31], v[210:211]
.Lat_nr_24:
	s_waitcnt vmcnt(0)
	s_barrier
	ds_read_b64_tr_b16 v[220:221], v127 offset:20480
	ds_read_b64_tr_b16 v[222:223], v127 offset:20992
	ds_read_b64_tr_b16 v[228:229], v127 offset:24576
	ds_read_b64_tr_b16 v[230:231], v127 offset:25088
	v_max_f32_e32 v149, v80, v81
	v_sub_f32_e32 v80, v80, v174
	v_sub_f32_e32 v81, v81, v174
	v_exp_f32_e32 v80, v80
	v_exp_f32_e32 v81, v81
	v_mov_b32_e32 v176, v80
	v_mov_b32_e32 v177, v81
	v_cvt_pk_bf16_f32 v80, v80, v81
	v_max3_f32 v149, v149, v82, v83
	v_sub_f32_e32 v82, v82, v174
	v_sub_f32_e32 v83, v83, v174
	v_exp_f32_e32 v82, v82
	ds_read_b64_tr_b16 v[224:225], v127 offset:21504
	ds_read_b64_tr_b16 v[226:227], v127 offset:22016
	v_exp_f32_e32 v83, v83
	v_add_f32_e32 v176, v82, v176
	v_add_f32_e32 v177, v83, v177
	v_cvt_pk_bf16_f32 v81, v82, v83
	v_max3_f32 v149, v149, v84, v85
	v_sub_f32_e32 v84, v84, v174
	v_sub_f32_e32 v85, v85, v174
	ds_read_b64_tr_b16 v[232:233], v127 offset:25600
	ds_read_b64_tr_b16 v[234:235], v127 offset:26112
	v_exp_f32_e32 v84, v84
	v_exp_f32_e32 v85, v85
	v_add_f32_e32 v176, v84, v176
	v_add_f32_e32 v177, v85, v177
	v_cvt_pk_bf16_f32 v82, v84, v85
	v_max3_f32 v149, v149, v86, v87
	v_sub_f32_e32 v86, v86, v174
	v_sub_f32_e32 v87, v87, v174
	v_exp_f32_e32 v86, v86
	v_exp_f32_e32 v87, v87
	v_add_f32_e32 v176, v86, v176
	v_add_f32_e32 v177, v87, v177
	v_cvt_pk_bf16_f32 v83, v86, v87
	v_max3_f32 v149, v149, v88, v89
	v_sub_f32_e32 v88, v88, v174
	v_sub_f32_e32 v89, v89, v174
	v_exp_f32_e32 v88, v88
	v_exp_f32_e32 v89, v89
	v_add_f32_e32 v176, v88, v176
	v_add_f32_e32 v177, v89, v177
	v_cvt_pk_bf16_f32 v84, v88, v89
	v_max3_f32 v149, v149, v90, v91
	v_sub_f32_e32 v90, v90, v174
	v_sub_f32_e32 v91, v91, v174
	v_exp_f32_e32 v90, v90
	v_exp_f32_e32 v91, v91
	v_add_f32_e32 v176, v90, v176
	v_add_f32_e32 v177, v91, v177
	s_waitcnt lgkmcnt(6)
	v_mfma_f32_32x32x16_bf16 v[0:15], v[80:83], v[220:223], v[0:15]
	ds_read_b64_tr_b16 v[236:237], v127 offset:22528
	ds_read_b64_tr_b16 v[238:239], v127 offset:23040
	v_cvt_pk_bf16_f32 v85, v90, v91
	v_max3_f32 v149, v149, v92, v93
	v_sub_f32_e32 v92, v92, v174
	v_sub_f32_e32 v93, v93, v174
	v_exp_f32_e32 v92, v92
	v_exp_f32_e32 v93, v93
	v_add_f32_e32 v176, v92, v176
	s_waitcnt lgkmcnt(6)
	v_mfma_f32_32x32x16_bf16 v[16:31], v[80:83], v[228:231], v[16:31]
	ds_read_b64_tr_b16 v[244:245], v127 offset:26624
	ds_read_b64_tr_b16 v[246:247], v127 offset:27136
	v_add_f32_e32 v177, v93, v177
	v_cvt_pk_bf16_f32 v86, v92, v93
	v_max3_f32 v149, v149, v94, v95
	v_sub_f32_e32 v94, v94, v174
	v_sub_f32_e32 v95, v95, v174
	v_exp_f32_e32 v94, v94
	v_exp_f32_e32 v95, v95
	v_add_f32_e32 v176, v94, v176
	v_add_f32_e32 v177, v95, v177
	v_cvt_pk_bf16_f32 v87, v94, v95
	v_max3_f32 v149, v149, v64, v65
	v_sub_f32_e32 v64, v64, v174
	v_sub_f32_e32 v65, v65, v174
	v_exp_f32_e32 v64, v64
	v_exp_f32_e32 v65, v65
	v_add_f32_e32 v176, v64, v176
	v_add_f32_e32 v177, v65, v177
	v_cvt_pk_bf16_f32 v64, v64, v65
	v_max3_f32 v149, v149, v66, v67
	v_sub_f32_e32 v66, v66, v174
	v_sub_f32_e32 v67, v67, v174
	v_exp_f32_e32 v66, v66
	v_exp_f32_e32 v67, v67
	v_add_f32_e32 v176, v66, v176
	v_add_f32_e32 v177, v67, v177
	v_cvt_pk_bf16_f32 v65, v66, v67
	v_max3_f32 v149, v149, v68, v69
	v_sub_f32_e32 v68, v68, v174
	s_waitcnt lgkmcnt(6)
	v_mfma_f32_32x32x16_bf16 v[0:15], v[84:87], v[224:227], v[0:15]
	ds_read_b64_tr_b16 v[240:241], v127 offset:23552
	ds_read_b64_tr_b16 v[242:243], v127 offset:24064
	v_sub_f32_e32 v69, v69, v174
	v_exp_f32_e32 v68, v68
	v_exp_f32_e32 v69, v69
	v_add_f32_e32 v176, v68, v176
	v_add_f32_e32 v177, v69, v177
	v_cvt_pk_bf16_f32 v66, v68, v69
	v_max3_f32 v149, v149, v70, v71
	s_waitcnt lgkmcnt(6)
	v_mfma_f32_32x32x16_bf16 v[16:31], v[84:87], v[232:235], v[16:31]
	ds_read_b64_tr_b16 v[122:123], v127 offset:27648
	ds_read_b64_tr_b16 v[124:125], v127 offset:28160
	v_sub_f32_e32 v70, v70, v174
	v_sub_f32_e32 v71, v71, v174
	v_exp_f32_e32 v70, v70
	v_exp_f32_e32 v71, v71
	v_add_f32_e32 v176, v70, v176
	v_add_f32_e32 v177, v71, v177
	v_cvt_pk_bf16_f32 v67, v70, v71
	v_max3_f32 v149, v149, v72, v73
	v_sub_f32_e32 v72, v72, v174
	v_sub_f32_e32 v73, v73, v174
	v_exp_f32_e32 v72, v72
	v_exp_f32_e32 v73, v73
	v_add_f32_e32 v176, v72, v176
	v_add_f32_e32 v177, v73, v177
	v_cvt_pk_bf16_f32 v68, v72, v73
	v_max3_f32 v149, v149, v74, v75
	v_sub_f32_e32 v74, v74, v174
	v_sub_f32_e32 v75, v75, v174
	v_exp_f32_e32 v74, v74
	v_exp_f32_e32 v75, v75
	v_add_f32_e32 v176, v74, v176
	s_waitcnt lgkmcnt(6)
	v_mfma_f32_32x32x16_bf16 v[0:15], v[64:67], v[236:239], v[0:15]
	v_add_f32_e32 v177, v75, v177
	v_cvt_pk_bf16_f32 v69, v74, v75
	v_max3_f32 v149, v149, v76, v77
	v_sub_f32_e32 v76, v76, v174
	v_sub_f32_e32 v77, v77, v174
	v_exp_f32_e32 v76, v76
	v_exp_f32_e32 v77, v77
	s_waitcnt lgkmcnt(4)
	v_mfma_f32_32x32x16_bf16 v[16:31], v[64:67], v[244:247], v[16:31]
	v_add_f32_e32 v176, v76, v176
	v_add_f32_e32 v177, v77, v177
	v_cvt_pk_bf16_f32 v70, v76, v77
	v_max3_f32 v149, v149, v78, v79
	v_sub_f32_e32 v78, v78, v174
	v_sub_f32_e32 v79, v79, v174
	v_exp_f32_e32 v78, v78
	v_exp_f32_e32 v79, v79
	v_add_f32_e32 v176, v78, v176
	v_add_f32_e32 v177, v79, v177
	v_cvt_pk_bf16_f32 v71, v78, v79
	v_add_f32_e32 v179, v176, v177
	v_mov_b32_e32 v175, v149
	v_mov_b32_e32 v178, v149
	v_add_f32_e32 v147, v147, v179
	s_nop 1
	v_permlane32_swap_b32_e32 v175, v178
	v_max_f32_e32 v175, v175, v178
	v_sub_f32_e32 v175, v175, v174
	v_cmp_lt_f32_e32 vcc, s43, v175
	s_waitcnt lgkmcnt(2)
	v_mfma_f32_32x32x16_bf16 v[0:15], v[68:71], v[240:243], v[0:15]
	s_waitcnt lgkmcnt(0)
	v_mfma_f32_32x32x16_bf16 v[16:31], v[68:71], v[122:125], v[16:31]
	s_cbranch_vccz .Lat_nr_25
	v_max_f32_e32 v175, v175, v175
	v_max_f32_e32 v175, 0, v175
	v_exp_f32_e64 v178, -v175
	s_and_saveexec_b64 s[4:5], s[2:3]
	ds_write_b32 v143, v178 offset:40960
	s_or_b64 exec, exec, s[4:5]
	s_waitcnt lgkmcnt(0)
	v_add_u32_e32 v179, s33, v191
	v_add_f32_e32 v174, v174, v175
	v_mul_f32_e32 v147, v147, v178
	ds_read_b128 v[196:199], v179 offset:40960
	ds_read_b128 v[200:203], v179 offset:40992
	ds_read_b128 v[204:207], v179 offset:41024
	ds_read_b128 v[208:211], v179 offset:41056
	s_waitcnt lgkmcnt(0)
	s_nop 15
	v_pk_mul_f32 v[0:1], v[0:1], v[196:197]
	v_pk_mul_f32 v[2:3], v[2:3], v[198:199]
	v_pk_mul_f32 v[4:5], v[4:5], v[200:201]
	v_pk_mul_f32 v[6:7], v[6:7], v[202:203]
	v_pk_mul_f32 v[8:9], v[8:9], v[204:205]
	v_pk_mul_f32 v[10:11], v[10:11], v[206:207]
	v_pk_mul_f32 v[12:13], v[12:13], v[208:209]
	v_pk_mul_f32 v[14:15], v[14:15], v[210:211]
	v_pk_mul_f32 v[16:17], v[16:17], v[196:197]
	v_pk_mul_f32 v[18:19], v[18:19], v[198:199]
	v_pk_mul_f32 v[20:21], v[20:21], v[200:201]
	v_pk_mul_f32 v[22:23], v[22:23], v[202:203]
	v_pk_mul_f32 v[24:25], v[24:25], v[204:205]
	v_pk_mul_f32 v[26:27], v[26:27], v[206:207]
	v_pk_mul_f32 v[28:29], v[28:29], v[208:209]
	v_pk_mul_f32 v[30:31], v[30:31], v[210:211]
.Lat_nr_25:
	s_waitcnt vmcnt(0)
	s_barrier
	v_mov_b32_e32 v32, v147
	s_mov_b32 s10, s27
